# prep token loop: the 3 bf16 loads of all 16 tokens issued up front, previous-token values reused from registers instead of being reloaded; per-token load waits removed
# speedup vs baseline: 1.0412x; 1.0070x over previous
; DI unsigned pack2(float a, float b) { f32v2 v = {a, b}; return __builtin_bit_cast(unsigned, __builtin_convertvector(v, bf16v2)); }
; DI void phase_prep(const PRef& p, int l) {
;     ...
;     const int c = tid & 255, half = tid >> 8, h = c >> 6;
;     {
;       float* lora = act + 32 * 128;
;       const int w8 = tid >> 6, ln = tid & 63, fr = ln & 15, fq = ln >> 4;
;       const u16* w2t = (const u16*)(p.ws + OFF_WT + WT_W2T);
;       const u16* a2t = (const u16*)(p.ws + OFF_WT + WT_A2T);
;       const u16* g2t = (const u16*)(p.ws + OFF_WT + WT_G2T);
; #pragma unroll
;       for (int nbi = 0; nbi < 2; ++nbi) {
;         const int col0 = (w8 * 2 + nbi) * 16;
;         const bf16x8 bw = *reinterpret_cast<const bf16x8*>(w2t + (size_t)(col0 + fr) * 32 + fq * 8);
;         const bf16x8 ba = *reinterpret_cast<const bf16x8*>(a2t + (size_t)(col0 + fr) * 32 + fq * 8);
;         const bf16x8 bg0 = *reinterpret_cast<const bf16x8*>(g2t + (size_t)(col0 + fr) * 64 + fq * 8);
;         const bf16x8 bg1 = *reinterpret_cast<const bf16x8*>(g2t + (size_t)(col0 + fr) * 64 + 32 + fq * 8);
; #pragma unroll
;         for (int mb = 0; mb < 2; ++mb) {
;           const float* ap = act + (mb * 16 + fr) * 128 + fq * 8;
;           bf16x8 af[4];
; #pragma unroll
;           for (int ks = 0; ks < 4; ++ks) {
;             const float4 f0 = *reinterpret_cast<const float4*>(ap + ks * 32), f1 = *reinterpret_cast<const float4*>(ap + ks * 32 + 4);
;             af[ks] = __builtin_bit_cast(bf16x8, (u32x4{pack2(f0.x, f0.y), pack2(f0.z, f0.w), pack2(f1.x, f1.y), pack2(f1.z, f1.w)}));
;           }
;           const f32x4 z4 = f32x4{0.f, 0.f, 0.f, 0.f};
;           f32x4 dw = __builtin_amdgcn_mfma_f32_16x16x32_bf16(bw, af[0], z4, 0, 0, 0);
;           f32x4 da = __builtin_amdgcn_mfma_f32_16x16x32_bf16(ba, af[1], z4, 0, 0, 0);
;           f32x4 dg = __builtin_amdgcn_mfma_f32_16x16x32_bf16(bg0, af[2], z4, 0, 0, 0);
;           dg = __builtin_amdgcn_mfma_f32_16x16x32_bf16(bg1, af[3], dg, 0, 0, 0);
;           float* lp = lora + (mb * 16 + fr) * 256 + col0 + fq * 4;
;           *reinterpret_cast<float4*>(lp) = make_float4(dw[0], dw[1], dw[2], dw[3]);
;           *reinterpret_cast<float4*>(lp + 32 * 256) = make_float4(da[0], da[1], da[2], da[3]);
;           *reinterpret_cast<float4*>(lp + 2 * 32 * 256) = make_float4(dg[0], dg[1], dg[2], dg[3]);
;         }
;       }
;     }
;     __syncthreads();
.LBB0_1076:
	s_or_b64 exec, exec, s[2:3]
	s_waitcnt lgkmcnt(0)
	s_barrier
	global_load_dwordx4 v[40:43], v[20:21], off
	global_load_dwordx4 v[44:47], v[22:23], off
	global_load_dwordx4 v[48:51], v[24:25], off
	global_load_dwordx4 v[52:55], v[24:25], off offset:64
	global_load_dwordx4 v[56:59], v[26:27], off
	s_waitcnt vmcnt(5)
	ds_read_b128 v[60:63], v102
	ds_read_b128 v[64:67], v102 offset:16
	global_load_dwordx4 v[68:71], v[28:29], off
	ds_read_b128 v[72:75], v102 offset:128
	ds_read_b128 v[104:107], v102 offset:144
	global_load_dwordx4 v[108:111], v[30:31], off
	ds_read_b128 v[112:115], v102 offset:256
	ds_read_b128 v[116:119], v102 offset:272
	ds_read_b128 v[120:123], v102 offset:384
	ds_read_b128 v[124:127], v102 offset:400
	global_load_dwordx4 v[128:131], v[30:31], off offset:64
	s_waitcnt lgkmcnt(7)
	v_cvt_pk_bf16_f32 v60, v60, v61
	v_cvt_pk_bf16_f32 v61, v62, v63
	s_waitcnt lgkmcnt(6)
	v_cvt_pk_bf16_f32 v62, v64, v65
	s_waitcnt lgkmcnt(5)
	v_cvt_pk_bf16_f32 v64, v72, v73
	v_cvt_pk_bf16_f32 v65, v74, v75
	s_waitcnt lgkmcnt(3)
	v_cvt_pk_bf16_f32 v72, v112, v113
	v_cvt_pk_bf16_f32 v73, v114, v115
	s_waitcnt lgkmcnt(2)
	v_cvt_pk_bf16_f32 v74, v116, v117
	v_cvt_pk_bf16_f32 v75, v118, v119
	v_cvt_pk_bf16_f32 v63, v66, v67
	v_cvt_pk_bf16_f32 v66, v104, v105
	v_cvt_pk_bf16_f32 v67, v106, v107
	s_waitcnt lgkmcnt(1)
	v_cvt_pk_bf16_f32 v104, v120, v121
	v_cvt_pk_bf16_f32 v105, v122, v123
	s_waitcnt lgkmcnt(0)
	v_cvt_pk_bf16_f32 v106, v124, v125
	v_cvt_pk_bf16_f32 v107, v126, v127
	v_mov_b32_e32 v133, 0
	v_mov_b32_e32 v132, 0
	v_mov_b32_e32 v134, 0
	s_waitcnt vmcnt(7)
	v_mfma_f32_16x16x32_bf16 v[60:63], v[40:43], v[60:63], 0
	s_waitcnt vmcnt(5)
	v_mfma_f32_16x16x32_bf16 v[72:75], v[48:51], v[72:75], 0
	v_mfma_f32_16x16x32_bf16 v[64:67], v[44:47], v[64:67], 0
	s_waitcnt vmcnt(4)
	v_mfma_f32_16x16x32_bf16 v[72:75], v[52:55], v[104:107], v[72:75]
	s_nop 2
	ds_write_b128 v80, v[60:63] offset:16384
	s_nop 1
	ds_write_b128 v80, v[64:67] offset:49152
	s_nop 0
	ds_write_b128 v81, v[72:75]
	ds_read_b128 v[60:63], v103
	ds_read_b128 v[64:67], v103 offset:16
	ds_read_b128 v[72:75], v103 offset:128
	ds_read_b128 v[104:107], v103 offset:144
	ds_read_b128 v[112:115], v103 offset:256
	ds_read_b128 v[116:119], v103 offset:272
	ds_read_b128 v[120:123], v103 offset:384
	ds_read_b128 v[124:127], v103 offset:400
	s_waitcnt lgkmcnt(7)
	v_cvt_pk_bf16_f32 v60, v60, v61
	v_cvt_pk_bf16_f32 v61, v62, v63
	s_waitcnt lgkmcnt(6)
	v_cvt_pk_bf16_f32 v62, v64, v65
	v_cvt_pk_bf16_f32 v63, v66, v67
	s_waitcnt lgkmcnt(5)
	v_cvt_pk_bf16_f32 v64, v72, v73
	v_cvt_pk_bf16_f32 v65, v74, v75
	v_mfma_f32_16x16x32_bf16 v[40:43], v[40:43], v[60:63], 0
	s_waitcnt lgkmcnt(3)
	v_cvt_pk_bf16_f32 v60, v112, v113
	v_cvt_pk_bf16_f32 v61, v114, v115
	s_waitcnt lgkmcnt(2)
	v_cvt_pk_bf16_f32 v62, v116, v117
	v_cvt_pk_bf16_f32 v63, v118, v119
	v_cvt_pk_bf16_f32 v66, v104, v105
	v_cvt_pk_bf16_f32 v67, v106, v107
	v_mfma_f32_16x16x32_bf16 v[48:51], v[48:51], v[60:63], 0
	s_nop 0
	v_mfma_f32_16x16x32_bf16 v[44:47], v[44:47], v[64:67], 0
	s_waitcnt lgkmcnt(1)
	v_cvt_pk_bf16_f32 v64, v120, v121
	v_cvt_pk_bf16_f32 v65, v122, v123
	s_waitcnt lgkmcnt(0)
	v_cvt_pk_bf16_f32 v66, v124, v125
	v_cvt_pk_bf16_f32 v67, v126, v127
	s_nop 1
	v_mfma_f32_16x16x32_bf16 v[48:51], v[52:55], v[64:67], v[48:51]
	ds_write_b128 v82, v[40:43] offset:16384
	ds_write_b128 v82, v[44:47] offset:49152
	s_nop 5
	ds_write_b128 v83, v[48:51]
	ds_read_b128 v[40:43], v102
	ds_read_b128 v[44:47], v102 offset:16
	ds_read_b128 v[48:51], v102 offset:128
	ds_read_b128 v[52:55], v102 offset:144
	ds_read_b128 v[60:63], v102 offset:256
	ds_read_b128 v[64:67], v102 offset:272
	ds_read_b128 v[72:75], v102 offset:384
	ds_read_b128 v[104:107], v102 offset:400
	s_waitcnt lgkmcnt(7)
	v_cvt_pk_bf16_f32 v40, v40, v41
	v_cvt_pk_bf16_f32 v41, v42, v43
	s_waitcnt lgkmcnt(6)
	v_cvt_pk_bf16_f32 v42, v44, v45
	s_waitcnt lgkmcnt(5)
	v_cvt_pk_bf16_f32 v44, v48, v49
	v_cvt_pk_bf16_f32 v45, v50, v51
	s_waitcnt lgkmcnt(3)
	v_cvt_pk_bf16_f32 v48, v60, v61
	v_cvt_pk_bf16_f32 v49, v62, v63
	s_waitcnt lgkmcnt(2)
	v_cvt_pk_bf16_f32 v50, v64, v65
	v_cvt_pk_bf16_f32 v51, v66, v67
	v_cvt_pk_bf16_f32 v43, v46, v47
	v_cvt_pk_bf16_f32 v46, v52, v53
	s_waitcnt vmcnt(1)
	v_mfma_f32_16x16x32_bf16 v[48:51], v[108:111], v[48:51], 0
	v_cvt_pk_bf16_f32 v47, v54, v55
	s_waitcnt lgkmcnt(1)
	v_cvt_pk_bf16_f32 v52, v72, v73
	v_cvt_pk_bf16_f32 v53, v74, v75
	v_mfma_f32_16x16x32_bf16 v[40:43], v[56:59], v[40:43], 0
	s_waitcnt lgkmcnt(0)
	v_cvt_pk_bf16_f32 v54, v104, v105
	v_cvt_pk_bf16_f32 v55, v106, v107
	v_mfma_f32_16x16x32_bf16 v[44:47], v[68:71], v[44:47], 0
	s_waitcnt vmcnt(0)
	v_mfma_f32_16x16x32_bf16 v[48:51], v[128:131], v[52:55], v[48:51]
	s_nop 1
	ds_write_b128 v80, v[40:43] offset:16448
	s_nop 2
	ds_write_b128 v80, v[44:47] offset:49216
	s_nop 0
	ds_write_b128 v84, v[48:51]
	ds_read_b128 v[40:43], v103
	ds_read_b128 v[44:47], v103 offset:16
	ds_read_b128 v[48:51], v103 offset:128
	ds_read_b128 v[52:55], v103 offset:144
	ds_read_b128 v[60:63], v103 offset:256
	ds_read_b128 v[64:67], v103 offset:272
	ds_read_b128 v[72:75], v103 offset:384
	ds_read_b128 v[104:107], v103 offset:400
	s_waitcnt lgkmcnt(7)
	v_cvt_pk_bf16_f32 v40, v40, v41
	v_cvt_pk_bf16_f32 v41, v42, v43
	s_waitcnt lgkmcnt(6)
	v_cvt_pk_bf16_f32 v42, v44, v45
	s_waitcnt lgkmcnt(5)
	v_cvt_pk_bf16_f32 v44, v48, v49
	v_cvt_pk_bf16_f32 v45, v50, v51
	s_waitcnt lgkmcnt(3)
	v_cvt_pk_bf16_f32 v48, v60, v61
	v_cvt_pk_bf16_f32 v49, v62, v63
	s_waitcnt lgkmcnt(2)
	v_cvt_pk_bf16_f32 v50, v64, v65
	v_cvt_pk_bf16_f32 v51, v66, v67
	v_cvt_pk_bf16_f32 v43, v46, v47
	v_cvt_pk_bf16_f32 v46, v52, v53
	v_mfma_f32_16x16x32_bf16 v[48:51], v[108:111], v[48:51], 0
	v_cvt_pk_bf16_f32 v47, v54, v55
	s_waitcnt lgkmcnt(1)
	v_cvt_pk_bf16_f32 v52, v72, v73
	v_cvt_pk_bf16_f32 v53, v74, v75
	v_mfma_f32_16x16x32_bf16 v[40:43], v[56:59], v[40:43], 0
	s_waitcnt lgkmcnt(0)
	v_cvt_pk_bf16_f32 v54, v104, v105
	v_cvt_pk_bf16_f32 v55, v106, v107
	v_mfma_f32_16x16x32_bf16 v[44:47], v[68:71], v[44:47], 0
	s_nop 0
	v_mfma_f32_16x16x32_bf16 v[48:51], v[128:131], v[52:55], v[48:51]
	s_nop 1
	ds_write_b128 v82, v[40:43] offset:16448
	s_nop 2
	ds_write_b128 v82, v[44:47] offset:49216
	s_nop 0
	ds_write_b128 v85, v[48:51]
	s_waitcnt lgkmcnt(0)
	s_barrier
; DI float bf2f(u16 h) { return __uint_as_float(((unsigned)h) << 16); }
; DI void phase_prep(const PRef& p, int l) {
;     ...
;     const float mur = mu[c], muk = mu[256 + c], muv = mu[512 + c];
;     const float w0c = w0[c], a0c = a0[c], kkc = k_k[c], kac = k_a[c], rkc = r_k[c];
; #pragma unroll
;     for (int i = 0; i < 16; ++i) {
;       const int tok = tk0 + half * 16 + i;
;       const bool has_prev = (tok & (SEQ - 1)) != 0;
;       const u16* pr_ = rw + (size_t)tok * 896;
;       float r0 = bf2f(pr_[c]), k0 = bf2f(pr_[256 + c]), v0 = bf2f(pr_[512 + c]);
;       float r1 = 0.f, k1 = 0.f, v1 = 0.f;
;       if (has_prev) { r1 = bf2f(pr_[c - 896]); k1 = bf2f(pr_[256 + c - 896]); v1 = bf2f(pr_[512 + c - 896]); }
	global_load_dword v105, v[0:1], off
	global_load_dword v106, v[0:1], off offset:1024
	global_load_dword v107, v[0:1], off offset:2048
	global_load_dword v112, v[2:3], off
	global_load_dword v111, v[4:5], off
	global_load_dword v108, v[6:7], off
	global_load_dword v110, v[8:9], off
	global_load_dword v104, v[10:11], off
	v_add_u32_e32 v42, s19, v79
	v_mad_i64_i32 v[74:75], s[2:3], v42, s79, v[34:35]
	global_load_ushort v129, v[74:75], off
	global_load_ushort v130, v[74:75], off offset:512
	global_load_ushort v131, v[74:75], off offset:1024
	s_mov_b32 s2, 0xe00
	s_mov_b32 s3, 0
	global_load_ushort v160, v[74:75], off
	global_load_ushort v161, v[74:75], off offset:512
	global_load_ushort v162, v[74:75], off offset:1024
	global_load_ushort v163, v[74:75], off offset:1792
	global_load_ushort v164, v[74:75], off offset:2304
	global_load_ushort v165, v[74:75], off offset:2816
	v_lshl_add_u64 v[208:209], s[2:3], 0, v[74:75]
	global_load_ushort v166, v[208:209], off
	global_load_ushort v167, v[208:209], off offset:512
	global_load_ushort v168, v[208:209], off offset:1024
	global_load_ushort v169, v[208:209], off offset:1792
	global_load_ushort v170, v[208:209], off offset:2304
	global_load_ushort v171, v[208:209], off offset:2816
	v_lshl_add_u64 v[208:209], s[2:3], 0, v[208:209]
	global_load_ushort v172, v[208:209], off
	global_load_ushort v173, v[208:209], off offset:512
	global_load_ushort v174, v[208:209], off offset:1024
	global_load_ushort v175, v[208:209], off offset:1792
	global_load_ushort v176, v[208:209], off offset:2304
	global_load_ushort v177, v[208:209], off offset:2816
	v_lshl_add_u64 v[208:209], s[2:3], 0, v[208:209]
	global_load_ushort v178, v[208:209], off
	global_load_ushort v179, v[208:209], off offset:512
	global_load_ushort v180, v[208:209], off offset:1024
	global_load_ushort v181, v[208:209], off offset:1792
	global_load_ushort v182, v[208:209], off offset:2304
	global_load_ushort v183, v[208:209], off offset:2816
	v_lshl_add_u64 v[208:209], s[2:3], 0, v[208:209]
	global_load_ushort v184, v[208:209], off
	global_load_ushort v185, v[208:209], off offset:512
	global_load_ushort v186, v[208:209], off offset:1024
	global_load_ushort v187, v[208:209], off offset:1792
	global_load_ushort v188, v[208:209], off offset:2304
	global_load_ushort v189, v[208:209], off offset:2816
	v_lshl_add_u64 v[208:209], s[2:3], 0, v[208:209]
	global_load_ushort v190, v[208:209], off
	global_load_ushort v191, v[208:209], off offset:512
	global_load_ushort v192, v[208:209], off offset:1024
	global_load_ushort v193, v[208:209], off offset:1792
	global_load_ushort v194, v[208:209], off offset:2304
	global_load_ushort v195, v[208:209], off offset:2816
	v_lshl_add_u64 v[208:209], s[2:3], 0, v[208:209]
	global_load_ushort v196, v[208:209], off
	global_load_ushort v197, v[208:209], off offset:512
	global_load_ushort v198, v[208:209], off offset:1024
	global_load_ushort v199, v[208:209], off offset:1792
	global_load_ushort v200, v[208:209], off offset:2304
	global_load_ushort v201, v[208:209], off offset:2816
	v_lshl_add_u64 v[208:209], s[2:3], 0, v[208:209]
	global_load_ushort v202, v[208:209], off
	global_load_ushort v203, v[208:209], off offset:512
	global_load_ushort v204, v[208:209], off offset:1024
	global_load_ushort v205, v[208:209], off offset:1792
	global_load_ushort v206, v[208:209], off offset:2304
	global_load_ushort v207, v[208:209], off offset:2816
	ds_read2st64_b32 v[72:73], v78 offset0:64 offset1:68
	ds_read2st64_b32 v[70:71], v78 offset0:192 offset1:196
	ds_read2st64_b32 v[68:69], v78 offset0:72 offset1:76
	ds_read2st64_b32 v[66:67], v78 offset0:200 offset1:204
	ds_read2st64_b32 v[64:65], v78 offset0:80 offset1:84
	ds_read2st64_b32 v[62:63], v78 offset0:208 offset1:212
	ds_read2st64_b32 v[60:61], v78 offset0:88 offset1:92
	ds_read2st64_b32 v[58:59], v78 offset0:216 offset1:220
	ds_read_b32 v127, v86
	ds_read_b32 v126, v87
	ds_read_b32 v125, v88
	ds_read_b32 v124, v89
	ds_read_b32 v123, v90
	ds_read_b32 v122, v91
	ds_read_b32 v121, v92
	ds_read_b32 v120, v93
	ds_read2st64_b32 v[56:57], v78 offset0:96 offset1:100
	ds_read2st64_b32 v[54:55], v78 offset0:224 offset1:228
	ds_read2st64_b32 v[52:53], v78 offset0:104 offset1:108
	ds_read2st64_b32 v[50:51], v78 offset0:232 offset1:236
	ds_read2st64_b32 v[48:49], v78 offset0:112 offset1:116
	ds_read2st64_b32 v[46:47], v78 offset0:240 offset1:244
	ds_read2st64_b32 v[44:45], v78 offset0:120 offset1:124
	ds_read2st64_b32 v[40:41], v78 offset0:248 offset1:252
	ds_read_b32 v119, v94
	ds_read_b32 v118, v95
	ds_read_b32 v117, v96
	ds_read_b32 v116, v97
	ds_read_b32 v115, v98
	ds_read_b32 v114, v99
	ds_read_b32 v113, v100
	ds_read_b32 v109, v101
	v_and_b32_e32 v128, 0xff0, v42
	v_cmp_ne_u32_e32 vcc, 0, v128
	s_and_saveexec_b64 s[2:3], vcc
	s_cbranch_execz .LBB0_1078
	global_load_ushort v43, v[74:75], off offset:-1792
	global_load_ushort v132, v[74:75], off offset:-768
	s_nop 0
	global_load_ushort v74, v[74:75], off offset:-1280
	s_waitcnt vmcnt(2)
	v_lshlrev_b32_e32 v133, 16, v43
	s_waitcnt vmcnt(1)
	v_lshlrev_b32_e32 v132, 16, v132
	s_waitcnt vmcnt(0)
	v_lshlrev_b32_e32 v134, 16, v74

; DI u16 f2bf(float x) { return (u16)(pack2(x, 0.f) & 0xffffu); }
; DI float bf2f(u16 h) { return __uint_as_float(((unsigned)h) << 16); }
; DI float sigmoidf_(float x) { return 1.f / (1.f + __expf(-x)); }
; DI void phase_prep(const PRef& p, int l) {
;     ...
;     for (int i = 0; i < 16; ++i) {
;       const int tok = tk0 + half * 16 + i;
;       const bool has_prev = (tok & (SEQ - 1)) != 0;
;       const u16* pr_ = rw + (size_t)tok * 896;
;       float r0 = bf2f(pr_[c]), k0 = bf2f(pr_[256 + c]), v0 = bf2f(pr_[512 + c]);
;       float r1 = 0.f, k1 = 0.f, v1 = 0.f;
;       if (has_prev) { r1 = bf2f(pr_[c - 896]); k1 = bf2f(pr_[256 + c - 896]); v1 = bf2f(pr_[512 + c - 896]); }
;       float r = r0 + (r1 - r0) * mur, k = k0 + (k1 - k0) * muk, v = v0 + (v1 - v0) * muv;
;       float w = __expf(-0.6065306597126334f * sigmoidf_(w0c + accw[i]));
;       float a = sigmoidf_(a0c + acca[i]);
;       float kk = k * kkc;
;       float ss = wave_sum(kk * kk);
;       kk *= rsqrtf(fmaxf(ss, 1e-24f));
;       float kp = k * (1.f + (a - 1.f) * kac);
;       float bb = kk * a;
;       float bo = wave_sum(r * kp * rkc);
;       const int b = tok >> 12, t = tok & (SEQ - 1);
;       char* rp = rec + ((size_t)((b * 4 + h) * SEQ + t)) * 1152;
;       const int cc = c & 63;
;       reinterpret_cast<float*>(rp)[cc] = w;
;       reinterpret_cast<float*>(rp + 256)[cc] = kk;
;       reinterpret_cast<float*>(rp + 512)[cc] = bb;
;       reinterpret_cast<u16*>(rp + 768)[cc] = f2bf(kp);
;       reinterpret_cast<u16*>(rp + 896)[cc] = f2bf(r);
;       reinterpret_cast<u16*>(rp + 1024)[cc] = f2bf(v);
;       gbuf[(size_t)tok * 256 + c] = f2bf(accg[i]);
;       if (cc == 0) bonus[(size_t)tok * 4 + h] = bo;
.LBB0_1080:
	s_or_b64 exec, exec, s[4:5]
	v_or_b32_e32 v70, 1, v42
	v_mad_i64_i32 v[128:129], s[2:3], v70, s79, v[34:35]
	v_add_f32_e32 v72, v73, v112
	v_mul_f32_e32 v72, 0xbfb8aa3b, v72
	v_add_f32_e32 v73, v71, v111
	v_exp_f32_e32 v133, v72
	v_mul_f32_e32 v73, 0xbfb8aa3b, v73
	v_exp_f32_e32 v134, v73
	s_movk_i32 s2, 0xff1
	v_add_f32_e32 v133, 1.0, v133
	v_and_or_b32 v128, v70, s2, v74
	v_div_scale_f32 v135, s[2:3], v133, v133, 1.0
	v_add_f32_e32 v134, 1.0, v134
	v_rcp_f32_e32 v138, v135
	v_div_scale_f32 v137, s[2:3], v134, v134, 1.0
	v_rcp_f32_e32 v139, v137
	v_fma_f32 v141, -v135, v138, 1.0
	v_div_scale_f32 v136, vcc, 1.0, v133, 1.0
	v_fmac_f32_e32 v138, v141, v138
	v_fma_f32 v142, -v137, v139, 1.0
	v_mul_f32_e32 v141, v136, v138
	v_div_scale_f32 v140, s[14:15], 1.0, v134, 1.0
	v_fmac_f32_e32 v139, v142, v139
	v_fma_f32 v143, -v135, v141, v136
	v_mul_f32_e32 v142, v140, v139
	v_fmac_f32_e32 v141, v143, v138
	v_fma_f32 v144, -v137, v142, v140
	v_fma_f32 v135, -v135, v141, v136
	v_fmac_f32_e32 v142, v144, v139
	v_div_fmas_f32 v135, v135, v138, v141
	v_fma_f32 v136, -v137, v142, v140
	v_div_fixup_f32 v133, v135, v133, 1.0
	s_mov_b64 vcc, s[14:15]
	v_div_fmas_f32 v135, v136, v139, v142
	v_mul_f32_e32 v133, 0xbf1b4598, v133
	v_mul_f32_e32 v133, 0x3fb8aa3b, v133
	v_div_fixup_f32 v134, v135, v134, 1.0
	v_exp_f32_e32 v133, v133
	v_add_f32_e32 v135, -1.0, v134
	v_fma_f32 v135, v110, v135, 1.0
	v_mad_i64_i32 v[72:73], s[2:3], v128, s52, v[36:37]
	v_lshl_add_u64 v[128:129], v[72:73], 0, v[38:39]
	global_store_dword v[72:73], v133, off
	v_ashrrev_i32_e32 v71, 31, v70
	v_lshlrev_b32_e32 v43, 16, v163
	v_lshlrev_b32_e32 v75, 16, v164
	v_lshlrev_b32_e32 v127, 16, v165
	v_lshlrev_b32_e32 v130, 16, v162
	v_lshlrev_b32_e32 v131, 16, v161
	v_sub_f32_e32 v131, v131, v75
	v_sub_f32_e32 v130, v130, v127
	v_fmac_f32_e32 v75, v106, v131
	v_fmac_f32_e32 v127, v107, v130
	v_mul_f32_e32 v130, v108, v75
	v_mul_f32_e32 v131, v130, v130
	v_lshlrev_b32_e32 v132, 16, v160
	v_sub_f32_e32 v132, v132, v43
	v_mov_b32_dpp v131, v131 quad_perm:[1,0,3,2] row_mask:0xf bank_mask:0xf bound_ctrl:1
	v_fmac_f32_e32 v131, v130, v130
	v_fmac_f32_e32 v43, v105, v132
	v_mul_f32_e32 v75, v135, v75
	v_add_f32_dpp v131, v131, v131 quad_perm:[2,3,0,1] row_mask:0xf bank_mask:0xf bound_ctrl:1
	v_mul_f32_e32 v132, v43, v75
	v_cvt_pk_bf16_f32 v75, v75, s0
	v_add_f32_dpp v131, v131, v131 row_half_mirror row_mask:0xf bank_mask:0xf bound_ctrl:1
	v_mul_f32_e32 v133, v104, v132
	global_store_short v[128:129], v75, off offset:768
	v_add_f32_dpp v131, v131, v131 row_mirror row_mask:0xf bank_mask:0xf bound_ctrl:1
	v_mov_b32_dpp v75, v133 quad_perm:[1,0,3,2] row_mask:0xf bank_mask:0xf bound_ctrl:1
	v_readlane_b32 s2, v131, 16
	v_readlane_b32 s5, v131, 48
	v_fmac_f32_e32 v75, v104, v132
	v_readlane_b32 s3, v131, 0
	v_readlane_b32 s4, v131, 32
	v_mov_b32_e32 v131, s2
	v_mov_b32_e32 v132, s5
	v_add_f32_e32 v131, s3, v131
	v_add_f32_e32 v132, s4, v132
	v_add_f32_e32 v131, v131, v132
	v_max_f32_e32 v131, 0x179abe15, v131
	v_rsq_f32_e32 v131, v131
	v_add_f32_dpp v75, v75, v75 quad_perm:[2,3,0,1] row_mask:0xf bank_mask:0xf bound_ctrl:1
	v_cvt_pk_bf16_f32 v43, v43, s0
	s_nop 0
	v_add_f32_dpp v75, v75, v75 row_half_mirror row_mask:0xf bank_mask:0xf bound_ctrl:1
	s_nop 1
	v_add_f32_dpp v75, v75, v75 row_mirror row_mask:0xf bank_mask:0xf bound_ctrl:1
	s_nop 0
	v_readlane_b32 s2, v75, 0
	v_readlane_b32 s14, v75, 16
	v_readlane_b32 s3, v75, 32
	v_readlane_b32 s15, v75, 48
	v_mul_f32_e32 v75, v130, v131
	v_mul_f32_e32 v130, v134, v75
	global_store_dword v[72:73], v75, off offset:256
	global_store_dword v[72:73], v130, off offset:512
	global_store_short v[128:129], v43, off offset:896
	v_cvt_pk_bf16_f32 v43, v127, s0
	v_lshlrev_b64 v[72:73], 9, v[70:71]
	global_store_short v[128:129], v43, off offset:1024
	v_cvt_pk_bf16_f32 v43, v126, s0
	v_lshl_add_u64 v[72:73], v[12:13], 0, v[72:73]
	global_store_short v[72:73], v43, off
	s_and_saveexec_b64 s[4:5], s[8:9]
	s_cbranch_execz .LBB0_1082
	v_mov_b32_e32 v72, s14
	v_mov_b32_e32 v73, s15
	v_pk_add_f32 v[72:73], s[2:3], v[72:73]
	v_lshl_add_u64 v[70:71], v[70:71], 4, v[14:15]
	v_add_f32_e32 v43, v72, v73
	global_store_dword v[70:71], v43, off
.LBB0_1082:
	s_or_b64 exec, exec, s[4:5]
	v_or_b32_e32 v70, 2, v42
	v_mad_i64_i32 v[72:73], s[2:3], v70, s79, v[34:35]
	v_add_f32_e32 v68, v68, v112
	v_mul_f32_e32 v68, 0xbfb8aa3b, v68
	v_exp_f32_e32 v68, v68
	s_movk_i32 s2, 0xff2
	v_and_or_b32 v72, v70, s2, v74
	v_add_f32_e32 v66, v66, v111
	v_add_f32_e32 v68, 1.0, v68
	v_div_scale_f32 v132, s[2:3], v68, v68, 1.0
	v_rcp_f32_e32 v135, v132
	v_mul_f32_e32 v66, 0xbfb8aa3b, v66
	v_exp_f32_e32 v66, v66
	v_div_scale_f32 v133, vcc, 1.0, v68, 1.0
	v_fma_f32 v138, -v132, v135, 1.0
	v_fmac_f32_e32 v135, v138, v135
	v_mul_f32_e32 v138, v133, v135
	v_fma_f32 v140, -v132, v138, v133
	v_fmac_f32_e32 v138, v140, v135
	v_add_f32_e32 v66, 1.0, v66
	v_fma_f32 v132, -v132, v138, v133
	v_div_scale_f32 v134, s[2:3], v66, v66, 1.0
	v_div_fmas_f32 v132, v132, v135, v138
	v_rcp_f32_e32 v136, v134
	v_div_fixup_f32 v68, v132, v68, 1.0
	v_mul_f32_e32 v68, 0xbf1b4598, v68
	v_mul_f32_e32 v68, 0x3fb8aa3b, v68
	v_exp_f32_e32 v68, v68
	v_fma_f32 v139, -v134, v136, 1.0
	v_div_scale_f32 v137, s[14:15], 1.0, v66, 1.0
	v_fmac_f32_e32 v136, v139, v136
	v_mad_i64_i32 v[72:73], s[2:3], v72, s52, v[36:37]
	v_mul_f32_e32 v139, v137, v136
	v_fma_f32 v141, -v134, v139, v137
	global_store_dword v[72:73], v68, off
	v_fmac_f32_e32 v139, v141, v136
	v_fma_f32 v133, -v134, v139, v137
	s_mov_b64 vcc, s[14:15]
	v_div_fmas_f32 v132, v133, v136, v139
	v_div_fixup_f32 v66, v132, v66, 1.0
	v_add_f32_e32 v132, -1.0, v66
; DI u16 f2bf(float x) { return (u16)(pack2(x, 0.f) & 0xffffu); }
; DI float bf2f(u16 h) { return __uint_as_float(((unsigned)h) << 16); }
; DI float sigmoidf_(float x) { return 1.f / (1.f + __expf(-x)); }
; DI void phase_prep(const PRef& p, int l) {
;     ...
;     for (int i = 0; i < 16; ++i) {
;       const int tok = tk0 + half * 16 + i;
;       const bool has_prev = (tok & (SEQ - 1)) != 0;
;       const u16* pr_ = rw + (size_t)tok * 896;
;       float r0 = bf2f(pr_[c]), k0 = bf2f(pr_[256 + c]), v0 = bf2f(pr_[512 + c]);
;       float r1 = 0.f, k1 = 0.f, v1 = 0.f;
;       if (has_prev) { r1 = bf2f(pr_[c - 896]); k1 = bf2f(pr_[256 + c - 896]); v1 = bf2f(pr_[512 + c - 896]); }
;       float r = r0 + (r1 - r0) * mur, k = k0 + (k1 - k0) * muk, v = v0 + (v1 - v0) * muv;
;       float w = __expf(-0.6065306597126334f * sigmoidf_(w0c + accw[i]));
;       float a = sigmoidf_(a0c + acca[i]);
;       float kk = k * kkc;
;       float ss = wave_sum(kk * kk);
;       kk *= rsqrtf(fmaxf(ss, 1e-24f));
;       float kp = k * (1.f + (a - 1.f) * kac);
;       float bb = kk * a;
;       float bo = wave_sum(r * kp * rkc);
;       const int b = tok >> 12, t = tok & (SEQ - 1);
;       char* rp = rec + ((size_t)((b * 4 + h) * SEQ + t)) * 1152;
;       const int cc = c & 63;
;       reinterpret_cast<float*>(rp)[cc] = w;
;       reinterpret_cast<float*>(rp + 256)[cc] = kk;
;       reinterpret_cast<float*>(rp + 512)[cc] = bb;
;       reinterpret_cast<u16*>(rp + 768)[cc] = f2bf(kp);
;       reinterpret_cast<u16*>(rp + 896)[cc] = f2bf(r);
;       reinterpret_cast<u16*>(rp + 1024)[cc] = f2bf(v);
;       gbuf[(size_t)tok * 256 + c] = f2bf(accg[i]);
;       if (cc == 0) bonus[(size_t)tok * 4 + h] = bo;
	v_fma_f32 v132, v110, v132, 1.0
	v_lshl_add_u64 v[126:127], v[72:73], 0, v[38:39]
	v_ashrrev_i32_e32 v71, 31, v70
	v_lshlrev_b32_e32 v43, 16, v166
	v_lshlrev_b32_e32 v68, 16, v167
	v_lshlrev_b32_e32 v75, 16, v168
	v_lshlrev_b32_e32 v128, 16, v165
	v_lshlrev_b32_e32 v129, 16, v164
	v_sub_f32_e32 v129, v129, v68
	v_sub_f32_e32 v128, v128, v75
	v_fmac_f32_e32 v68, v106, v129
	v_fmac_f32_e32 v75, v107, v128
	v_mul_f32_e32 v128, v108, v68
	v_mul_f32_e32 v129, v128, v128
	v_lshlrev_b32_e32 v130, 16, v163
	v_sub_f32_e32 v130, v130, v43
	v_mov_b32_dpp v129, v129 quad_perm:[1,0,3,2] row_mask:0xf bank_mask:0xf bound_ctrl:1
	v_fmac_f32_e32 v129, v128, v128
	v_fmac_f32_e32 v43, v105, v130
	v_mul_f32_e32 v68, v132, v68
	v_add_f32_dpp v129, v129, v129 quad_perm:[2,3,0,1] row_mask:0xf bank_mask:0xf bound_ctrl:1
	v_mul_f32_e32 v130, v43, v68
	v_cvt_pk_bf16_f32 v68, v68, s0
	v_add_f32_dpp v129, v129, v129 row_half_mirror row_mask:0xf bank_mask:0xf bound_ctrl:1
	v_mul_f32_e32 v131, v104, v130
	global_store_short v[126:127], v68, off offset:768
	v_add_f32_dpp v129, v129, v129 row_mirror row_mask:0xf bank_mask:0xf bound_ctrl:1
	v_mov_b32_dpp v68, v131 quad_perm:[1,0,3,2] row_mask:0xf bank_mask:0xf bound_ctrl:1
	v_readlane_b32 s2, v129, 16
	v_readlane_b32 s5, v129, 48
	v_fmac_f32_e32 v68, v104, v130
	v_readlane_b32 s3, v129, 0
	v_readlane_b32 s4, v129, 32
	v_mov_b32_e32 v129, s2
	v_mov_b32_e32 v130, s5
	v_add_f32_e32 v129, s3, v129
	v_add_f32_e32 v130, s4, v130
	v_add_f32_e32 v129, v129, v130
	v_max_f32_e32 v129, 0x179abe15, v129
	v_rsq_f32_e32 v129, v129
	v_add_f32_dpp v68, v68, v68 quad_perm:[2,3,0,1] row_mask:0xf bank_mask:0xf bound_ctrl:1
	v_cvt_pk_bf16_f32 v43, v43, s0
	s_nop 0
	v_add_f32_dpp v68, v68, v68 row_half_mirror row_mask:0xf bank_mask:0xf bound_ctrl:1
	s_nop 1
	v_add_f32_dpp v68, v68, v68 row_mirror row_mask:0xf bank_mask:0xf bound_ctrl:1
	s_nop 0
	v_readlane_b32 s2, v68, 0
	v_readlane_b32 s14, v68, 16
	v_readlane_b32 s3, v68, 32
	v_readlane_b32 s15, v68, 48
	v_mul_f32_e32 v68, v128, v129
	v_mul_f32_e32 v66, v66, v68
	global_store_dword v[72:73], v68, off offset:256
	global_store_dword v[72:73], v66, off offset:512
	global_store_short v[126:127], v43, off offset:896
	v_cvt_pk_bf16_f32 v43, v75, s0
	v_lshlrev_b64 v[72:73], 9, v[70:71]
	global_store_short v[126:127], v43, off offset:1024
	v_cvt_pk_bf16_f32 v43, v125, s0
	v_lshl_add_u64 v[72:73], v[12:13], 0, v[72:73]
	global_store_short v[72:73], v43, off
	s_and_saveexec_b64 s[4:5], s[8:9]
	s_cbranch_execz .LBB0_1084
	v_mov_b32_e32 v72, s14
	v_mov_b32_e32 v73, s15
	v_pk_add_f32 v[72:73], s[2:3], v[72:73]
	v_lshl_add_u64 v[70:71], v[70:71], 4, v[14:15]
	v_add_f32_e32 v43, v72, v73
	global_store_dword v[70:71], v43, off
.LBB0_1084:
	s_or_b64 exec, exec, s[4:5]
	v_or_b32_e32 v66, 3, v42
	v_mad_i64_i32 v[70:71], s[2:3], v66, s79, v[34:35]
	v_add_f32_e32 v68, v69, v112
	v_mul_f32_e32 v68, 0xbfb8aa3b, v68
	v_add_f32_e32 v69, v67, v111
	v_exp_f32_e32 v127, v68
	v_mul_f32_e32 v69, 0xbfb8aa3b, v69
	v_exp_f32_e32 v128, v69
	s_movk_i32 s2, 0xff3
	v_add_f32_e32 v127, 1.0, v127
	v_and_or_b32 v70, v66, s2, v74
	v_div_scale_f32 v129, s[2:3], v127, v127, 1.0
	v_add_f32_e32 v128, 1.0, v128
	v_rcp_f32_e32 v132, v129
	v_div_scale_f32 v131, s[2:3], v128, v128, 1.0
	v_rcp_f32_e32 v133, v131
	v_fma_f32 v135, -v129, v132, 1.0
	v_div_scale_f32 v130, vcc, 1.0, v127, 1.0
	v_fmac_f32_e32 v132, v135, v132
	v_fma_f32 v136, -v131, v133, 1.0
	v_mul_f32_e32 v135, v130, v132
	v_div_scale_f32 v134, s[14:15], 1.0, v128, 1.0
	v_fmac_f32_e32 v133, v136, v133
	v_fma_f32 v137, -v129, v135, v130
	v_mul_f32_e32 v136, v134, v133
	v_fmac_f32_e32 v135, v137, v132
	v_fma_f32 v138, -v131, v136, v134
	v_fma_f32 v129, -v129, v135, v130
	v_fmac_f32_e32 v136, v138, v133
	v_div_fmas_f32 v129, v129, v132, v135
	v_fma_f32 v130, -v131, v136, v134
	v_div_fixup_f32 v127, v129, v127, 1.0
	s_mov_b64 vcc, s[14:15]
	v_div_fmas_f32 v129, v130, v133, v136
	v_mul_f32_e32 v127, 0xbf1b4598, v127
	v_mul_f32_e32 v127, 0x3fb8aa3b, v127
	v_div_fixup_f32 v128, v129, v128, 1.0
	v_exp_f32_e32 v127, v127
	v_add_f32_e32 v129, -1.0, v128
	v_fma_f32 v129, v110, v129, 1.0
	v_mad_i64_i32 v[68:69], s[2:3], v70, s52, v[36:37]
	v_lshl_add_u64 v[70:71], v[68:69], 0, v[38:39]
	global_store_dword v[68:69], v127, off
	v_ashrrev_i32_e32 v67, 31, v66
	v_lshlrev_b32_e32 v43, 16, v169
	v_lshlrev_b32_e32 v72, 16, v170
	v_lshlrev_b32_e32 v73, 16, v171
	v_lshlrev_b32_e32 v75, 16, v168
	v_lshlrev_b32_e32 v125, 16, v167
	v_sub_f32_e32 v125, v125, v72
	v_sub_f32_e32 v75, v75, v73
	v_fmac_f32_e32 v72, v106, v125
	v_fmac_f32_e32 v73, v107, v75
	v_mul_f32_e32 v75, v108, v72
	v_mul_f32_e32 v125, v75, v75
	v_lshlrev_b32_e32 v126, 16, v166
	v_sub_f32_e32 v126, v126, v43
	v_mov_b32_dpp v125, v125 quad_perm:[1,0,3,2] row_mask:0xf bank_mask:0xf bound_ctrl:1
	v_fmac_f32_e32 v125, v75, v75
	v_fmac_f32_e32 v43, v105, v126
	v_mul_f32_e32 v72, v129, v72
	v_add_f32_dpp v125, v125, v125 quad_perm:[2,3,0,1] row_mask:0xf bank_mask:0xf bound_ctrl:1
	v_mul_f32_e32 v126, v43, v72
	v_cvt_pk_bf16_f32 v72, v72, s0
	v_add_f32_dpp v125, v125, v125 row_half_mirror row_mask:0xf bank_mask:0xf bound_ctrl:1
	v_mul_f32_e32 v127, v104, v126
	global_store_short v[70:71], v72, off offset:768
	v_add_f32_dpp v125, v125, v125 row_mirror row_mask:0xf bank_mask:0xf bound_ctrl:1
	v_mov_b32_dpp v72, v127 quad_perm:[1,0,3,2] row_mask:0xf bank_mask:0xf bound_ctrl:1
	v_readlane_b32 s2, v125, 16
	v_readlane_b32 s5, v125, 48
	v_fmac_f32_e32 v72, v104, v126
	v_readlane_b32 s3, v125, 0
	v_readlane_b32 s4, v125, 32
	v_mov_b32_e32 v125, s2
	v_mov_b32_e32 v126, s5
	v_add_f32_e32 v125, s3, v125
	v_add_f32_e32 v126, s4, v126
	v_add_f32_e32 v125, v125, v126
	v_max_f32_e32 v125, 0x179abe15, v125
	v_rsq_f32_e32 v125, v125
	v_add_f32_dpp v72, v72, v72 quad_perm:[2,3,0,1] row_mask:0xf bank_mask:0xf bound_ctrl:1
	v_cvt_pk_bf16_f32 v43, v43, s0
	s_nop 0
	v_add_f32_dpp v72, v72, v72 row_half_mirror row_mask:0xf bank_mask:0xf bound_ctrl:1
	s_nop 1
	v_add_f32_dpp v72, v72, v72 row_mirror row_mask:0xf bank_mask:0xf bound_ctrl:1
	s_nop 0
	v_readlane_b32 s2, v72, 0
	v_readlane_b32 s14, v72, 16
	v_readlane_b32 s3, v72, 32
	v_readlane_b32 s15, v72, 48
	v_mul_f32_e32 v72, v75, v125
	v_mul_f32_e32 v75, v128, v72
	global_store_dword v[68:69], v72, off offset:256
	global_store_dword v[68:69], v75, off offset:512
	global_store_short v[70:71], v43, off offset:896
	v_cvt_pk_bf16_f32 v43, v73, s0
	v_lshlrev_b64 v[68:69], 9, v[66:67]
	global_store_short v[70:71], v43, off offset:1024
	v_cvt_pk_bf16_f32 v43, v124, s0
	v_lshl_add_u64 v[68:69], v[12:13], 0, v[68:69]
	global_store_short v[68:69], v43, off
	s_and_saveexec_b64 s[4:5], s[8:9]
	s_cbranch_execz .LBB0_1086
	v_mov_b32_e32 v68, s14
	v_mov_b32_e32 v69, s15
	v_pk_add_f32 v[68:69], s[2:3], v[68:69]
	v_lshl_add_u64 v[66:67], v[66:67], 4, v[14:15]
	v_add_f32_e32 v43, v68, v69
	global_store_dword v[66:67], v43, off
; DI u16 f2bf(float x) { return (u16)(pack2(x, 0.f) & 0xffffu); }
; DI float bf2f(u16 h) { return __uint_as_float(((unsigned)h) << 16); }
; DI float sigmoidf_(float x) { return 1.f / (1.f + __expf(-x)); }
; DI void phase_prep(const PRef& p, int l) {
;     ...
;     for (int i = 0; i < 16; ++i) {
;       const int tok = tk0 + half * 16 + i;
;       const bool has_prev = (tok & (SEQ - 1)) != 0;
;       const u16* pr_ = rw + (size_t)tok * 896;
;       float r0 = bf2f(pr_[c]), k0 = bf2f(pr_[256 + c]), v0 = bf2f(pr_[512 + c]);
;       float r1 = 0.f, k1 = 0.f, v1 = 0.f;
;       if (has_prev) { r1 = bf2f(pr_[c - 896]); k1 = bf2f(pr_[256 + c - 896]); v1 = bf2f(pr_[512 + c - 896]); }
;       float r = r0 + (r1 - r0) * mur, k = k0 + (k1 - k0) * muk, v = v0 + (v1 - v0) * muv;
;       float w = __expf(-0.6065306597126334f * sigmoidf_(w0c + accw[i]));
;       float a = sigmoidf_(a0c + acca[i]);
;       float kk = k * kkc;
;       float ss = wave_sum(kk * kk);
;       kk *= rsqrtf(fmaxf(ss, 1e-24f));
;       float kp = k * (1.f + (a - 1.f) * kac);
;       float bb = kk * a;
;       float bo = wave_sum(r * kp * rkc);
;       const int b = tok >> 12, t = tok & (SEQ - 1);
;       char* rp = rec + ((size_t)((b * 4 + h) * SEQ + t)) * 1152;
;       const int cc = c & 63;
;       reinterpret_cast<float*>(rp)[cc] = w;
;       reinterpret_cast<float*>(rp + 256)[cc] = kk;
;       reinterpret_cast<float*>(rp + 512)[cc] = bb;
;       reinterpret_cast<u16*>(rp + 768)[cc] = f2bf(kp);
;       reinterpret_cast<u16*>(rp + 896)[cc] = f2bf(r);
;       reinterpret_cast<u16*>(rp + 1024)[cc] = f2bf(v);
;       gbuf[(size_t)tok * 256 + c] = f2bf(accg[i]);
;       if (cc == 0) bonus[(size_t)tok * 4 + h] = bo;
.LBB0_1086:
	s_or_b64 exec, exec, s[4:5]
	v_or_b32_e32 v66, 4, v42
	v_mad_i64_i32 v[68:69], s[2:3], v66, s79, v[34:35]
	v_add_f32_e32 v64, v64, v112
	v_mul_f32_e32 v64, 0xbfb8aa3b, v64
	v_exp_f32_e32 v64, v64
	s_movk_i32 s2, 0xff4
	v_and_or_b32 v68, v66, s2, v74
	v_add_f32_e32 v62, v62, v111
	v_add_f32_e32 v64, 1.0, v64
	v_div_scale_f32 v126, s[2:3], v64, v64, 1.0
	v_rcp_f32_e32 v129, v126
	v_mul_f32_e32 v62, 0xbfb8aa3b, v62
	v_exp_f32_e32 v62, v62
	v_div_scale_f32 v127, vcc, 1.0, v64, 1.0
	v_fma_f32 v132, -v126, v129, 1.0
	v_fmac_f32_e32 v129, v132, v129
	v_mul_f32_e32 v132, v127, v129
	v_fma_f32 v134, -v126, v132, v127
	v_fmac_f32_e32 v132, v134, v129
	v_add_f32_e32 v62, 1.0, v62
	v_fma_f32 v126, -v126, v132, v127
	v_div_scale_f32 v128, s[2:3], v62, v62, 1.0
	v_div_fmas_f32 v126, v126, v129, v132
	v_rcp_f32_e32 v130, v128
	v_div_fixup_f32 v64, v126, v64, 1.0
	v_mul_f32_e32 v64, 0xbf1b4598, v64
	v_mul_f32_e32 v64, 0x3fb8aa3b, v64
	v_exp_f32_e32 v64, v64
	v_fma_f32 v133, -v128, v130, 1.0
	v_div_scale_f32 v131, s[14:15], 1.0, v62, 1.0
	v_fmac_f32_e32 v130, v133, v130
	v_mad_i64_i32 v[68:69], s[2:3], v68, s52, v[36:37]
	v_mul_f32_e32 v133, v131, v130
	v_fma_f32 v135, -v128, v133, v131
	global_store_dword v[68:69], v64, off
	v_fmac_f32_e32 v133, v135, v130
	v_fma_f32 v127, -v128, v133, v131
	s_mov_b64 vcc, s[14:15]
	v_div_fmas_f32 v126, v127, v130, v133
	v_div_fixup_f32 v62, v126, v62, 1.0
	v_add_f32_e32 v126, -1.0, v62
	v_fma_f32 v126, v110, v126, 1.0
	v_lshl_add_u64 v[70:71], v[68:69], 0, v[38:39]
	v_ashrrev_i32_e32 v67, 31, v66
	v_lshlrev_b32_e32 v43, 16, v172
	v_lshlrev_b32_e32 v64, 16, v173
	v_lshlrev_b32_e32 v72, 16, v174
	v_lshlrev_b32_e32 v73, 16, v171
	v_lshlrev_b32_e32 v75, 16, v170
	v_sub_f32_e32 v75, v75, v64
	v_sub_f32_e32 v73, v73, v72
	v_fmac_f32_e32 v64, v106, v75
	v_fmac_f32_e32 v72, v107, v73
	v_mul_f32_e32 v73, v108, v64
	v_mul_f32_e32 v75, v73, v73
	v_lshlrev_b32_e32 v124, 16, v169
	v_sub_f32_e32 v124, v124, v43
	v_mov_b32_dpp v75, v75 quad_perm:[1,0,3,2] row_mask:0xf bank_mask:0xf bound_ctrl:1
	v_fmac_f32_e32 v75, v73, v73
	v_fmac_f32_e32 v43, v105, v124
	v_mul_f32_e32 v64, v126, v64
	v_add_f32_dpp v75, v75, v75 quad_perm:[2,3,0,1] row_mask:0xf bank_mask:0xf bound_ctrl:1
	v_mul_f32_e32 v124, v43, v64
	v_cvt_pk_bf16_f32 v64, v64, s0
	v_add_f32_dpp v75, v75, v75 row_half_mirror row_mask:0xf bank_mask:0xf bound_ctrl:1
	v_mul_f32_e32 v125, v104, v124
	global_store_short v[70:71], v64, off offset:768
	v_add_f32_dpp v75, v75, v75 row_mirror row_mask:0xf bank_mask:0xf bound_ctrl:1
	v_mov_b32_dpp v64, v125 quad_perm:[1,0,3,2] row_mask:0xf bank_mask:0xf bound_ctrl:1
	v_readlane_b32 s2, v75, 16
	v_readlane_b32 s5, v75, 48
	v_fmac_f32_e32 v64, v104, v124
	v_readlane_b32 s3, v75, 0
	v_readlane_b32 s4, v75, 32
	v_mov_b32_e32 v75, s2
	v_mov_b32_e32 v124, s5
	v_add_f32_e32 v75, s3, v75
	v_add_f32_e32 v124, s4, v124
	v_add_f32_e32 v75, v75, v124
	v_max_f32_e32 v75, 0x179abe15, v75
	v_rsq_f32_e32 v75, v75
	v_add_f32_dpp v64, v64, v64 quad_perm:[2,3,0,1] row_mask:0xf bank_mask:0xf bound_ctrl:1
	v_cvt_pk_bf16_f32 v43, v43, s0
	s_nop 0
	v_add_f32_dpp v64, v64, v64 row_half_mirror row_mask:0xf bank_mask:0xf bound_ctrl:1
	s_nop 1
	v_add_f32_dpp v64, v64, v64 row_mirror row_mask:0xf bank_mask:0xf bound_ctrl:1
	s_nop 0
	v_readlane_b32 s2, v64, 0
	v_readlane_b32 s14, v64, 16
	v_readlane_b32 s3, v64, 32
	v_readlane_b32 s15, v64, 48
	v_mul_f32_e32 v64, v73, v75
	v_mul_f32_e32 v62, v62, v64
	global_store_dword v[68:69], v64, off offset:256
	global_store_dword v[68:69], v62, off offset:512
	global_store_short v[70:71], v43, off offset:896
	v_cvt_pk_bf16_f32 v43, v72, s0
	v_lshlrev_b64 v[68:69], 9, v[66:67]
	global_store_short v[70:71], v43, off offset:1024
	v_cvt_pk_bf16_f32 v43, v123, s0
	v_lshl_add_u64 v[68:69], v[12:13], 0, v[68:69]
	global_store_short v[68:69], v43, off
	s_and_saveexec_b64 s[4:5], s[8:9]
	s_cbranch_execz .LBB0_1088
	v_mov_b32_e32 v68, s14
	v_mov_b32_e32 v69, s15
	v_pk_add_f32 v[68:69], s[2:3], v[68:69]
	v_lshl_add_u64 v[66:67], v[66:67], 4, v[14:15]
	v_add_f32_e32 v43, v68, v69
	global_store_dword v[66:67], v43, off
.LBB0_1088:
	s_or_b64 exec, exec, s[4:5]
	v_or_b32_e32 v62, 5, v42
	v_mad_i64_i32 v[66:67], s[2:3], v62, s79, v[34:35]
	v_add_f32_e32 v64, v65, v112
	v_mul_f32_e32 v64, 0xbfb8aa3b, v64
	v_add_f32_e32 v65, v63, v111
	v_exp_f32_e32 v73, v64
	v_mul_f32_e32 v65, 0xbfb8aa3b, v65
	v_exp_f32_e32 v75, v65
	s_movk_i32 s2, 0xff5
	v_add_f32_e32 v73, 1.0, v73
	v_and_or_b32 v66, v62, s2, v74
	v_div_scale_f32 v123, s[2:3], v73, v73, 1.0
	v_add_f32_e32 v75, 1.0, v75
	v_rcp_f32_e32 v126, v123
	v_div_scale_f32 v125, s[2:3], v75, v75, 1.0
	v_rcp_f32_e32 v127, v125
	v_fma_f32 v129, -v123, v126, 1.0
	v_div_scale_f32 v124, vcc, 1.0, v73, 1.0
	v_fmac_f32_e32 v126, v129, v126
	v_fma_f32 v130, -v125, v127, 1.0
	v_mul_f32_e32 v129, v124, v126
	v_div_scale_f32 v128, s[14:15], 1.0, v75, 1.0
	v_fmac_f32_e32 v127, v130, v127
	v_fma_f32 v131, -v123, v129, v124
	v_mul_f32_e32 v130, v128, v127
	v_fmac_f32_e32 v129, v131, v126
	v_fma_f32 v132, -v125, v130, v128
	v_fma_f32 v123, -v123, v129, v124
	v_fmac_f32_e32 v130, v132, v127
	v_div_fmas_f32 v123, v123, v126, v129
	v_fma_f32 v124, -v125, v130, v128
	v_div_fixup_f32 v73, v123, v73, 1.0
	s_mov_b64 vcc, s[14:15]
	v_div_fmas_f32 v123, v124, v127, v130
	v_mul_f32_e32 v73, 0xbf1b4598, v73
	v_mul_f32_e32 v73, 0x3fb8aa3b, v73
	v_div_fixup_f32 v75, v123, v75, 1.0
	v_exp_f32_e32 v73, v73
	v_add_f32_e32 v123, -1.0, v75
	v_fma_f32 v123, v110, v123, 1.0
	v_mad_i64_i32 v[64:65], s[2:3], v66, s52, v[36:37]
	v_lshl_add_u64 v[66:67], v[64:65], 0, v[38:39]
	global_store_dword v[64:65], v73, off
; DI u16 f2bf(float x) { return (u16)(pack2(x, 0.f) & 0xffffu); }
; DI float bf2f(u16 h) { return __uint_as_float(((unsigned)h) << 16); }
; DI float sigmoidf_(float x) { return 1.f / (1.f + __expf(-x)); }
; DI void phase_prep(const PRef& p, int l) {
;     ...
;     for (int i = 0; i < 16; ++i) {
;       const int tok = tk0 + half * 16 + i;
;       const bool has_prev = (tok & (SEQ - 1)) != 0;
;       const u16* pr_ = rw + (size_t)tok * 896;
;       float r0 = bf2f(pr_[c]), k0 = bf2f(pr_[256 + c]), v0 = bf2f(pr_[512 + c]);
;       float r1 = 0.f, k1 = 0.f, v1 = 0.f;
;       if (has_prev) { r1 = bf2f(pr_[c - 896]); k1 = bf2f(pr_[256 + c - 896]); v1 = bf2f(pr_[512 + c - 896]); }
;       float r = r0 + (r1 - r0) * mur, k = k0 + (k1 - k0) * muk, v = v0 + (v1 - v0) * muv;
;       float w = __expf(-0.6065306597126334f * sigmoidf_(w0c + accw[i]));
;       float a = sigmoidf_(a0c + acca[i]);
;       float kk = k * kkc;
;       float ss = wave_sum(kk * kk);
;       kk *= rsqrtf(fmaxf(ss, 1e-24f));
;       float kp = k * (1.f + (a - 1.f) * kac);
;       float bb = kk * a;
;       float bo = wave_sum(r * kp * rkc);
;       const int b = tok >> 12, t = tok & (SEQ - 1);
;       char* rp = rec + ((size_t)((b * 4 + h) * SEQ + t)) * 1152;
;       const int cc = c & 63;
;       reinterpret_cast<float*>(rp)[cc] = w;
;       reinterpret_cast<float*>(rp + 256)[cc] = kk;
;       reinterpret_cast<float*>(rp + 512)[cc] = bb;
;       reinterpret_cast<u16*>(rp + 768)[cc] = f2bf(kp);
;       reinterpret_cast<u16*>(rp + 896)[cc] = f2bf(r);
;       reinterpret_cast<u16*>(rp + 1024)[cc] = f2bf(v);
;       gbuf[(size_t)tok * 256 + c] = f2bf(accg[i]);
;       if (cc == 0) bonus[(size_t)tok * 4 + h] = bo;
	v_ashrrev_i32_e32 v63, 31, v62
	v_lshlrev_b32_e32 v43, 16, v175
	v_lshlrev_b32_e32 v68, 16, v176
	v_lshlrev_b32_e32 v69, 16, v177
	v_lshlrev_b32_e32 v70, 16, v174
	v_lshlrev_b32_e32 v71, 16, v173
	v_sub_f32_e32 v71, v71, v68
	v_sub_f32_e32 v70, v70, v69
	v_fmac_f32_e32 v68, v106, v71
	v_fmac_f32_e32 v69, v107, v70
	v_mul_f32_e32 v70, v108, v68
	v_mul_f32_e32 v71, v70, v70
	v_lshlrev_b32_e32 v72, 16, v172
	v_sub_f32_e32 v72, v72, v43
	v_mov_b32_dpp v71, v71 quad_perm:[1,0,3,2] row_mask:0xf bank_mask:0xf bound_ctrl:1
	v_fmac_f32_e32 v71, v70, v70
	v_fmac_f32_e32 v43, v105, v72
	v_mul_f32_e32 v68, v123, v68
	v_add_f32_dpp v71, v71, v71 quad_perm:[2,3,0,1] row_mask:0xf bank_mask:0xf bound_ctrl:1
	v_mul_f32_e32 v72, v43, v68
	v_cvt_pk_bf16_f32 v68, v68, s0
	v_add_f32_dpp v71, v71, v71 row_half_mirror row_mask:0xf bank_mask:0xf bound_ctrl:1
	v_mul_f32_e32 v73, v104, v72
	global_store_short v[66:67], v68, off offset:768
	v_add_f32_dpp v71, v71, v71 row_mirror row_mask:0xf bank_mask:0xf bound_ctrl:1
	v_mov_b32_dpp v68, v73 quad_perm:[1,0,3,2] row_mask:0xf bank_mask:0xf bound_ctrl:1
	v_readlane_b32 s2, v71, 16
	v_readlane_b32 s5, v71, 48
	v_fmac_f32_e32 v68, v104, v72
	v_readlane_b32 s3, v71, 0
	v_readlane_b32 s4, v71, 32
	v_mov_b32_e32 v71, s2
	v_mov_b32_e32 v72, s5
	v_add_f32_e32 v71, s3, v71
	v_add_f32_e32 v72, s4, v72
	v_add_f32_e32 v71, v71, v72
	v_max_f32_e32 v71, 0x179abe15, v71
	v_rsq_f32_e32 v71, v71
	v_add_f32_dpp v68, v68, v68 quad_perm:[2,3,0,1] row_mask:0xf bank_mask:0xf bound_ctrl:1
	v_cvt_pk_bf16_f32 v43, v43, s0
	s_nop 0
	v_add_f32_dpp v68, v68, v68 row_half_mirror row_mask:0xf bank_mask:0xf bound_ctrl:1
	s_nop 1
	v_add_f32_dpp v68, v68, v68 row_mirror row_mask:0xf bank_mask:0xf bound_ctrl:1
	s_nop 0
	v_readlane_b32 s2, v68, 0
	v_readlane_b32 s14, v68, 16
	v_readlane_b32 s3, v68, 32
	v_readlane_b32 s15, v68, 48
	v_mul_f32_e32 v68, v70, v71
	v_mul_f32_e32 v70, v75, v68
	global_store_dword v[64:65], v68, off offset:256
	global_store_dword v[64:65], v70, off offset:512
	global_store_short v[66:67], v43, off offset:896
	v_cvt_pk_bf16_f32 v43, v69, s0
	v_lshlrev_b64 v[64:65], 9, v[62:63]
	global_store_short v[66:67], v43, off offset:1024
	v_cvt_pk_bf16_f32 v43, v122, s0
	v_lshl_add_u64 v[64:65], v[12:13], 0, v[64:65]
	global_store_short v[64:65], v43, off
	s_and_saveexec_b64 s[4:5], s[8:9]
	s_cbranch_execz .LBB0_1090
	v_mov_b32_e32 v64, s14
	v_mov_b32_e32 v65, s15
	v_pk_add_f32 v[64:65], s[2:3], v[64:65]
	v_lshl_add_u64 v[62:63], v[62:63], 4, v[14:15]
	v_add_f32_e32 v43, v64, v65
	global_store_dword v[62:63], v43, off
.LBB0_1090:
	s_or_b64 exec, exec, s[4:5]
	v_or_b32_e32 v62, 6, v42
	v_mad_i64_i32 v[64:65], s[2:3], v62, s79, v[34:35]
	v_add_f32_e32 v60, v60, v112
	v_mul_f32_e32 v60, 0xbfb8aa3b, v60
	v_exp_f32_e32 v60, v60
	s_movk_i32 s2, 0xff6
	v_and_or_b32 v64, v62, s2, v74
	v_add_f32_e32 v58, v58, v111
	v_add_f32_e32 v60, 1.0, v60
	v_div_scale_f32 v73, s[2:3], v60, v60, 1.0
	v_rcp_f32_e32 v123, v73
	v_mul_f32_e32 v58, 0xbfb8aa3b, v58
	v_exp_f32_e32 v58, v58
	v_div_scale_f32 v75, vcc, 1.0, v60, 1.0
	v_fma_f32 v126, -v73, v123, 1.0
	v_fmac_f32_e32 v123, v126, v123
	v_mul_f32_e32 v126, v75, v123
	v_fma_f32 v128, -v73, v126, v75
	v_fmac_f32_e32 v126, v128, v123
	v_add_f32_e32 v58, 1.0, v58
	v_fma_f32 v73, -v73, v126, v75
	v_div_scale_f32 v122, s[2:3], v58, v58, 1.0
	v_div_fmas_f32 v73, v73, v123, v126
	v_rcp_f32_e32 v124, v122
	v_div_fixup_f32 v60, v73, v60, 1.0
	v_mul_f32_e32 v60, 0xbf1b4598, v60
	v_mul_f32_e32 v60, 0x3fb8aa3b, v60
	v_exp_f32_e32 v60, v60
	v_fma_f32 v127, -v122, v124, 1.0
	v_div_scale_f32 v125, s[14:15], 1.0, v58, 1.0
	v_fmac_f32_e32 v124, v127, v124
	v_mad_i64_i32 v[64:65], s[2:3], v64, s52, v[36:37]
	v_mul_f32_e32 v127, v125, v124
	v_fma_f32 v129, -v122, v127, v125
	global_store_dword v[64:65], v60, off
	v_fmac_f32_e32 v127, v129, v124
	v_fma_f32 v75, -v122, v127, v125
	s_mov_b64 vcc, s[14:15]
	v_div_fmas_f32 v73, v75, v124, v127
	v_div_fixup_f32 v58, v73, v58, 1.0
	v_add_f32_e32 v73, -1.0, v58
	v_fma_f32 v73, v110, v73, 1.0
	v_lshl_add_u64 v[66:67], v[64:65], 0, v[38:39]
	v_ashrrev_i32_e32 v63, 31, v62
	v_lshlrev_b32_e32 v43, 16, v178
	v_lshlrev_b32_e32 v60, 16, v179
	v_lshlrev_b32_e32 v68, 16, v180
	v_lshlrev_b32_e32 v69, 16, v177
	v_lshlrev_b32_e32 v70, 16, v176
	v_sub_f32_e32 v70, v70, v60
	v_sub_f32_e32 v69, v69, v68
	v_fmac_f32_e32 v60, v106, v70
	v_fmac_f32_e32 v68, v107, v69
	v_mul_f32_e32 v69, v108, v60
	v_mul_f32_e32 v70, v69, v69
	v_lshlrev_b32_e32 v71, 16, v175
	v_sub_f32_e32 v71, v71, v43
	v_mov_b32_dpp v70, v70 quad_perm:[1,0,3,2] row_mask:0xf bank_mask:0xf bound_ctrl:1
	v_fmac_f32_e32 v70, v69, v69
	v_fmac_f32_e32 v43, v105, v71
	v_mul_f32_e32 v60, v73, v60
	v_add_f32_dpp v70, v70, v70 quad_perm:[2,3,0,1] row_mask:0xf bank_mask:0xf bound_ctrl:1
	v_mul_f32_e32 v71, v43, v60
	v_cvt_pk_bf16_f32 v60, v60, s0
	v_add_f32_dpp v70, v70, v70 row_half_mirror row_mask:0xf bank_mask:0xf bound_ctrl:1
	v_mul_f32_e32 v72, v104, v71
	global_store_short v[66:67], v60, off offset:768
	v_add_f32_dpp v70, v70, v70 row_mirror row_mask:0xf bank_mask:0xf bound_ctrl:1
	v_mov_b32_dpp v60, v72 quad_perm:[1,0,3,2] row_mask:0xf bank_mask:0xf bound_ctrl:1
	v_readlane_b32 s2, v70, 16
	v_readlane_b32 s5, v70, 48
	v_fmac_f32_e32 v60, v104, v71
	v_readlane_b32 s3, v70, 0
	v_readlane_b32 s4, v70, 32
	v_mov_b32_e32 v70, s2
	v_mov_b32_e32 v71, s5
	v_add_f32_e32 v70, s3, v70
	v_add_f32_e32 v71, s4, v71
	v_add_f32_e32 v70, v70, v71
	v_max_f32_e32 v70, 0x179abe15, v70
	v_rsq_f32_e32 v70, v70
	v_add_f32_dpp v60, v60, v60 quad_perm:[2,3,0,1] row_mask:0xf bank_mask:0xf bound_ctrl:1
	v_cvt_pk_bf16_f32 v43, v43, s0
	s_nop 0
	v_add_f32_dpp v60, v60, v60 row_half_mirror row_mask:0xf bank_mask:0xf bound_ctrl:1
	s_nop 1
	v_add_f32_dpp v60, v60, v60 row_mirror row_mask:0xf bank_mask:0xf bound_ctrl:1
	s_nop 0
	v_readlane_b32 s2, v60, 0
	v_readlane_b32 s14, v60, 16
	v_readlane_b32 s3, v60, 32
	v_readlane_b32 s15, v60, 48
	v_mul_f32_e32 v60, v69, v70
	v_mul_f32_e32 v58, v58, v60
	global_store_dword v[64:65], v60, off offset:256
	global_store_dword v[64:65], v58, off offset:512
	global_store_short v[66:67], v43, off offset:896
	v_cvt_pk_bf16_f32 v43, v68, s0
	v_lshlrev_b64 v[64:65], 9, v[62:63]
	global_store_short v[66:67], v43, off offset:1024
	v_cvt_pk_bf16_f32 v43, v121, s0
	v_lshl_add_u64 v[64:65], v[12:13], 0, v[64:65]
	global_store_short v[64:65], v43, off
	s_and_saveexec_b64 s[4:5], s[8:9]
	s_cbranch_execz .LBB0_1092
	v_mov_b32_e32 v64, s14
	v_mov_b32_e32 v65, s15
	v_pk_add_f32 v[64:65], s[2:3], v[64:65]
	v_lshl_add_u64 v[62:63], v[62:63], 4, v[14:15]
	v_add_f32_e32 v43, v64, v65
	global_store_dword v[62:63], v43, off
; DI u16 f2bf(float x) { return (u16)(pack2(x, 0.f) & 0xffffu); }
; DI float bf2f(u16 h) { return __uint_as_float(((unsigned)h) << 16); }
; DI float sigmoidf_(float x) { return 1.f / (1.f + __expf(-x)); }
; DI void phase_prep(const PRef& p, int l) {
;     ...
;     for (int i = 0; i < 16; ++i) {
;       const int tok = tk0 + half * 16 + i;
;       const bool has_prev = (tok & (SEQ - 1)) != 0;
;       const u16* pr_ = rw + (size_t)tok * 896;
;       float r0 = bf2f(pr_[c]), k0 = bf2f(pr_[256 + c]), v0 = bf2f(pr_[512 + c]);
;       float r1 = 0.f, k1 = 0.f, v1 = 0.f;
;       if (has_prev) { r1 = bf2f(pr_[c - 896]); k1 = bf2f(pr_[256 + c - 896]); v1 = bf2f(pr_[512 + c - 896]); }
;       float r = r0 + (r1 - r0) * mur, k = k0 + (k1 - k0) * muk, v = v0 + (v1 - v0) * muv;
;       float w = __expf(-0.6065306597126334f * sigmoidf_(w0c + accw[i]));
;       float a = sigmoidf_(a0c + acca[i]);
;       float kk = k * kkc;
;       float ss = wave_sum(kk * kk);
;       kk *= rsqrtf(fmaxf(ss, 1e-24f));
;       float kp = k * (1.f + (a - 1.f) * kac);
;       float bb = kk * a;
;       float bo = wave_sum(r * kp * rkc);
;       const int b = tok >> 12, t = tok & (SEQ - 1);
;       char* rp = rec + ((size_t)((b * 4 + h) * SEQ + t)) * 1152;
;       const int cc = c & 63;
;       reinterpret_cast<float*>(rp)[cc] = w;
;       reinterpret_cast<float*>(rp + 256)[cc] = kk;
;       reinterpret_cast<float*>(rp + 512)[cc] = bb;
;       reinterpret_cast<u16*>(rp + 768)[cc] = f2bf(kp);
;       reinterpret_cast<u16*>(rp + 896)[cc] = f2bf(r);
;       reinterpret_cast<u16*>(rp + 1024)[cc] = f2bf(v);
;       gbuf[(size_t)tok * 256 + c] = f2bf(accg[i]);
;       if (cc == 0) bonus[(size_t)tok * 4 + h] = bo;
.LBB0_1092:
	s_or_b64 exec, exec, s[4:5]
	v_or_b32_e32 v58, 7, v42
	v_mad_i64_i32 v[62:63], s[2:3], v58, s79, v[34:35]
	v_add_f32_e32 v60, v61, v112
	v_mul_f32_e32 v60, 0xbfb8aa3b, v60
	v_add_f32_e32 v61, v59, v111
	v_exp_f32_e32 v69, v60
	v_mul_f32_e32 v61, 0xbfb8aa3b, v61
	v_exp_f32_e32 v70, v61
	s_movk_i32 s2, 0xff7
	v_add_f32_e32 v69, 1.0, v69
	v_and_or_b32 v62, v58, s2, v74
	v_div_scale_f32 v71, s[2:3], v69, v69, 1.0
	v_add_f32_e32 v70, 1.0, v70
	v_rcp_f32_e32 v75, v71
	v_div_scale_f32 v73, s[2:3], v70, v70, 1.0
	v_rcp_f32_e32 v121, v73
	v_fma_f32 v123, -v71, v75, 1.0
	v_div_scale_f32 v72, vcc, 1.0, v69, 1.0
	v_fmac_f32_e32 v75, v123, v75
	v_fma_f32 v124, -v73, v121, 1.0
	v_mul_f32_e32 v123, v72, v75
	v_div_scale_f32 v122, s[14:15], 1.0, v70, 1.0
	v_fmac_f32_e32 v121, v124, v121
	v_fma_f32 v125, -v71, v123, v72
	v_mul_f32_e32 v124, v122, v121
	v_fmac_f32_e32 v123, v125, v75
	v_fma_f32 v126, -v73, v124, v122
	v_fma_f32 v71, -v71, v123, v72
	v_fmac_f32_e32 v124, v126, v121
	v_div_fmas_f32 v71, v71, v75, v123
	v_fma_f32 v72, -v73, v124, v122
	v_div_fixup_f32 v69, v71, v69, 1.0
	s_mov_b64 vcc, s[14:15]
	v_div_fmas_f32 v71, v72, v121, v124
	v_mul_f32_e32 v69, 0xbf1b4598, v69
	v_mul_f32_e32 v69, 0x3fb8aa3b, v69
	v_div_fixup_f32 v70, v71, v70, 1.0
	v_exp_f32_e32 v69, v69
	v_add_f32_e32 v71, -1.0, v70
	v_fma_f32 v71, v110, v71, 1.0
	v_mad_i64_i32 v[60:61], s[2:3], v62, s52, v[36:37]
	v_lshl_add_u64 v[62:63], v[60:61], 0, v[38:39]
	global_store_dword v[60:61], v69, off
	v_ashrrev_i32_e32 v59, 31, v58
	v_lshlrev_b32_e32 v43, 16, v181
	v_lshlrev_b32_e32 v64, 16, v182
	v_lshlrev_b32_e32 v65, 16, v183
	v_lshlrev_b32_e32 v66, 16, v180
	v_lshlrev_b32_e32 v67, 16, v179
	v_sub_f32_e32 v67, v67, v64
	v_sub_f32_e32 v66, v66, v65
	v_fmac_f32_e32 v64, v106, v67
	v_fmac_f32_e32 v65, v107, v66
	v_mul_f32_e32 v66, v108, v64
	v_mul_f32_e32 v67, v66, v66
	v_lshlrev_b32_e32 v68, 16, v178
	v_sub_f32_e32 v68, v68, v43
	v_mov_b32_dpp v67, v67 quad_perm:[1,0,3,2] row_mask:0xf bank_mask:0xf bound_ctrl:1
	v_fmac_f32_e32 v67, v66, v66
	v_fmac_f32_e32 v43, v105, v68
	v_mul_f32_e32 v64, v71, v64
	v_add_f32_dpp v67, v67, v67 quad_perm:[2,3,0,1] row_mask:0xf bank_mask:0xf bound_ctrl:1
	v_mul_f32_e32 v68, v43, v64
	v_cvt_pk_bf16_f32 v64, v64, s0
	v_add_f32_dpp v67, v67, v67 row_half_mirror row_mask:0xf bank_mask:0xf bound_ctrl:1
	v_mul_f32_e32 v69, v104, v68
	global_store_short v[62:63], v64, off offset:768
	v_add_f32_dpp v67, v67, v67 row_mirror row_mask:0xf bank_mask:0xf bound_ctrl:1
	v_mov_b32_dpp v64, v69 quad_perm:[1,0,3,2] row_mask:0xf bank_mask:0xf bound_ctrl:1
	v_readlane_b32 s2, v67, 16
	v_readlane_b32 s5, v67, 48
	v_fmac_f32_e32 v64, v104, v68
	v_readlane_b32 s3, v67, 0
	v_readlane_b32 s4, v67, 32
	v_mov_b32_e32 v67, s2
	v_mov_b32_e32 v68, s5
	v_add_f32_e32 v67, s3, v67
	v_add_f32_e32 v68, s4, v68
	v_add_f32_e32 v67, v67, v68
	v_max_f32_e32 v67, 0x179abe15, v67
	v_rsq_f32_e32 v67, v67
	v_add_f32_dpp v64, v64, v64 quad_perm:[2,3,0,1] row_mask:0xf bank_mask:0xf bound_ctrl:1
	v_cvt_pk_bf16_f32 v43, v43, s0
	s_nop 0
	v_add_f32_dpp v64, v64, v64 row_half_mirror row_mask:0xf bank_mask:0xf bound_ctrl:1
	s_nop 1
	v_add_f32_dpp v64, v64, v64 row_mirror row_mask:0xf bank_mask:0xf bound_ctrl:1
	s_nop 0
	v_readlane_b32 s2, v64, 0
	v_readlane_b32 s14, v64, 16
	v_readlane_b32 s3, v64, 32
	v_readlane_b32 s15, v64, 48
	v_mul_f32_e32 v64, v66, v67
	v_mul_f32_e32 v66, v70, v64
	global_store_dword v[60:61], v64, off offset:256
	global_store_dword v[60:61], v66, off offset:512
	global_store_short v[62:63], v43, off offset:896
	v_cvt_pk_bf16_f32 v43, v65, s0
	v_lshlrev_b64 v[60:61], 9, v[58:59]
	global_store_short v[62:63], v43, off offset:1024
	v_cvt_pk_bf16_f32 v43, v120, s0
	v_lshl_add_u64 v[60:61], v[12:13], 0, v[60:61]
	global_store_short v[60:61], v43, off
	s_and_saveexec_b64 s[4:5], s[8:9]
	s_cbranch_execz .LBB0_1094
	v_mov_b32_e32 v60, s14
	v_mov_b32_e32 v61, s15
	v_pk_add_f32 v[60:61], s[2:3], v[60:61]
	v_lshl_add_u64 v[58:59], v[58:59], 4, v[14:15]
	v_add_f32_e32 v43, v60, v61
	global_store_dword v[58:59], v43, off
.LBB0_1094:
	s_or_b64 exec, exec, s[4:5]
	v_or_b32_e32 v58, 8, v42
	v_mad_i64_i32 v[60:61], s[2:3], v58, s79, v[34:35]
	v_add_f32_e32 v56, v56, v112
	v_mul_f32_e32 v56, 0xbfb8aa3b, v56
	v_exp_f32_e32 v56, v56
	s_movk_i32 s2, 0xff8
	v_and_or_b32 v60, v58, s2, v74
	v_add_f32_e32 v54, v54, v111
	v_add_f32_e32 v56, 1.0, v56
	v_div_scale_f32 v69, s[2:3], v56, v56, 1.0
	v_rcp_f32_e32 v72, v69
	v_mul_f32_e32 v54, 0xbfb8aa3b, v54
	v_exp_f32_e32 v54, v54
	v_div_scale_f32 v70, vcc, 1.0, v56, 1.0
	v_fma_f32 v120, -v69, v72, 1.0
	v_fmac_f32_e32 v72, v120, v72
	v_mul_f32_e32 v120, v70, v72
	v_fma_f32 v122, -v69, v120, v70
	v_fmac_f32_e32 v120, v122, v72
	v_add_f32_e32 v54, 1.0, v54
	v_fma_f32 v69, -v69, v120, v70
	v_div_scale_f32 v71, s[2:3], v54, v54, 1.0
	v_div_fmas_f32 v69, v69, v72, v120
	v_rcp_f32_e32 v73, v71
	v_div_fixup_f32 v56, v69, v56, 1.0
	v_mul_f32_e32 v56, 0xbf1b4598, v56
	v_mul_f32_e32 v56, 0x3fb8aa3b, v56
	v_exp_f32_e32 v56, v56
	v_fma_f32 v121, -v71, v73, 1.0
	v_div_scale_f32 v75, s[14:15], 1.0, v54, 1.0
	v_fmac_f32_e32 v73, v121, v73
	v_mad_i64_i32 v[60:61], s[2:3], v60, s52, v[36:37]
	v_mul_f32_e32 v121, v75, v73
	v_fma_f32 v123, -v71, v121, v75
	global_store_dword v[60:61], v56, off
	v_fmac_f32_e32 v121, v123, v73
	v_fma_f32 v70, -v71, v121, v75
	s_mov_b64 vcc, s[14:15]
	v_div_fmas_f32 v69, v70, v73, v121
	v_div_fixup_f32 v54, v69, v54, 1.0
	v_add_f32_e32 v69, -1.0, v54
	v_fma_f32 v69, v110, v69, 1.0
	v_lshl_add_u64 v[62:63], v[60:61], 0, v[38:39]
	v_ashrrev_i32_e32 v59, 31, v58
	v_lshlrev_b32_e32 v43, 16, v184
	v_lshlrev_b32_e32 v56, 16, v185
; DI u16 f2bf(float x) { return (u16)(pack2(x, 0.f) & 0xffffu); }
; DI float bf2f(u16 h) { return __uint_as_float(((unsigned)h) << 16); }
; DI float sigmoidf_(float x) { return 1.f / (1.f + __expf(-x)); }
; DI void phase_prep(const PRef& p, int l) {
;     ...
; #pragma unroll
;     for (int i = 0; i < 16; ++i) {
;       const int tok = tk0 + half * 16 + i;
;       const bool has_prev = (tok & (SEQ - 1)) != 0;
;       const u16* pr_ = rw + (size_t)tok * 896;
;       float r0 = bf2f(pr_[c]), k0 = bf2f(pr_[256 + c]), v0 = bf2f(pr_[512 + c]);
;       float r1 = 0.f, k1 = 0.f, v1 = 0.f;
;       if (has_prev) { r1 = bf2f(pr_[c - 896]); k1 = bf2f(pr_[256 + c - 896]); v1 = bf2f(pr_[512 + c - 896]); }
;       float r = r0 + (r1 - r0) * mur, k = k0 + (k1 - k0) * muk, v = v0 + (v1 - v0) * muv;
;       float w = __expf(-0.6065306597126334f * sigmoidf_(w0c + accw[i]));
;       float a = sigmoidf_(a0c + acca[i]);
;       float kk = k * kkc;
;       float ss = wave_sum(kk * kk);
;       kk *= rsqrtf(fmaxf(ss, 1e-24f));
;       float kp = k * (1.f + (a - 1.f) * kac);
;       float bb = kk * a;
;       float bo = wave_sum(r * kp * rkc);
;       const int b = tok >> 12, t = tok & (SEQ - 1);
;       char* rp = rec + ((size_t)((b * 4 + h) * SEQ + t)) * 1152;
;       const int cc = c & 63;
;       reinterpret_cast<float*>(rp)[cc] = w;
;       reinterpret_cast<float*>(rp + 256)[cc] = kk;
;       reinterpret_cast<float*>(rp + 512)[cc] = bb;
;       reinterpret_cast<u16*>(rp + 768)[cc] = f2bf(kp);
;       reinterpret_cast<u16*>(rp + 896)[cc] = f2bf(r);
;       reinterpret_cast<u16*>(rp + 1024)[cc] = f2bf(v);
;       gbuf[(size_t)tok * 256 + c] = f2bf(accg[i]);
;       if (cc == 0) bonus[(size_t)tok * 4 + h] = bo;
	v_lshlrev_b32_e32 v64, 16, v186
	v_lshlrev_b32_e32 v65, 16, v183
	v_lshlrev_b32_e32 v66, 16, v182
	v_sub_f32_e32 v66, v66, v56
	v_sub_f32_e32 v65, v65, v64
	v_fmac_f32_e32 v56, v106, v66
	v_fmac_f32_e32 v64, v107, v65
	v_mul_f32_e32 v65, v108, v56
	v_mul_f32_e32 v66, v65, v65
	v_lshlrev_b32_e32 v67, 16, v181
	v_sub_f32_e32 v67, v67, v43
	v_mov_b32_dpp v66, v66 quad_perm:[1,0,3,2] row_mask:0xf bank_mask:0xf bound_ctrl:1
	v_fmac_f32_e32 v66, v65, v65
	v_fmac_f32_e32 v43, v105, v67
	v_mul_f32_e32 v56, v69, v56
	v_add_f32_dpp v66, v66, v66 quad_perm:[2,3,0,1] row_mask:0xf bank_mask:0xf bound_ctrl:1
	v_mul_f32_e32 v67, v43, v56
	v_cvt_pk_bf16_f32 v56, v56, s0
	v_add_f32_dpp v66, v66, v66 row_half_mirror row_mask:0xf bank_mask:0xf bound_ctrl:1
	v_mul_f32_e32 v68, v104, v67
	global_store_short v[62:63], v56, off offset:768
	v_add_f32_dpp v66, v66, v66 row_mirror row_mask:0xf bank_mask:0xf bound_ctrl:1
	v_mov_b32_dpp v56, v68 quad_perm:[1,0,3,2] row_mask:0xf bank_mask:0xf bound_ctrl:1
	v_readlane_b32 s2, v66, 16
	v_readlane_b32 s5, v66, 48
	v_fmac_f32_e32 v56, v104, v67
	v_readlane_b32 s3, v66, 0
	v_readlane_b32 s4, v66, 32
	v_mov_b32_e32 v66, s2
	v_mov_b32_e32 v67, s5
	v_add_f32_e32 v66, s3, v66
	v_add_f32_e32 v67, s4, v67
	v_add_f32_e32 v66, v66, v67
	v_max_f32_e32 v66, 0x179abe15, v66
	v_rsq_f32_e32 v66, v66
	v_add_f32_dpp v56, v56, v56 quad_perm:[2,3,0,1] row_mask:0xf bank_mask:0xf bound_ctrl:1
	v_cvt_pk_bf16_f32 v43, v43, s0
	s_nop 0
	v_add_f32_dpp v56, v56, v56 row_half_mirror row_mask:0xf bank_mask:0xf bound_ctrl:1
	s_nop 1
	v_add_f32_dpp v56, v56, v56 row_mirror row_mask:0xf bank_mask:0xf bound_ctrl:1
	s_nop 0
	v_readlane_b32 s2, v56, 0
	v_readlane_b32 s14, v56, 16
	v_readlane_b32 s3, v56, 32
	v_readlane_b32 s15, v56, 48
	v_mul_f32_e32 v56, v65, v66
	v_mul_f32_e32 v54, v54, v56
	global_store_dword v[60:61], v56, off offset:256
	global_store_dword v[60:61], v54, off offset:512
	global_store_short v[62:63], v43, off offset:896
	v_cvt_pk_bf16_f32 v43, v64, s0
	v_lshlrev_b64 v[60:61], 9, v[58:59]
	global_store_short v[62:63], v43, off offset:1024
	s_waitcnt lgkmcnt(7)
	v_cvt_pk_bf16_f32 v43, v119, s0
	v_lshl_add_u64 v[60:61], v[12:13], 0, v[60:61]
	global_store_short v[60:61], v43, off
	s_and_saveexec_b64 s[4:5], s[8:9]
	s_cbranch_execz .LBB0_1096
	v_mov_b32_e32 v60, s14
	v_mov_b32_e32 v61, s15
	v_pk_add_f32 v[60:61], s[2:3], v[60:61]
	v_lshl_add_u64 v[58:59], v[58:59], 4, v[14:15]
	v_add_f32_e32 v43, v60, v61
	global_store_dword v[58:59], v43, off
.LBB0_1096:
	s_or_b64 exec, exec, s[4:5]
	v_or_b32_e32 v58, 9, v42
	v_mad_i64_i32 v[60:61], s[2:3], v58, s79, v[34:35]
	v_add_f32_e32 v57, v57, v112
	v_mul_f32_e32 v57, 0xbfb8aa3b, v57
	v_exp_f32_e32 v57, v57
	v_add_f32_e32 v55, v55, v111
	v_mul_f32_e32 v55, 0xbfb8aa3b, v55
	v_exp_f32_e32 v55, v55
	v_add_f32_e32 v57, 1.0, v57
	v_ashrrev_i32_e32 v59, 31, v58
	v_add_f32_e32 v55, 1.0, v55
	v_lshlrev_b32_e32 v43, 16, v187
	v_lshlrev_b32_e32 v54, 16, v188
	v_lshlrev_b32_e32 v56, 16, v189
	v_lshlrev_b32_e32 v62, 16, v186
	v_lshlrev_b32_e32 v63, 16, v185
	v_lshlrev_b32_e32 v60, 16, v184
	v_sub_f32_e32 v60, v60, v43
	v_fmac_f32_e32 v43, v105, v60
	v_sub_f32_e32 v60, v63, v54
	v_fmac_f32_e32 v54, v106, v60
	v_sub_f32_e32 v60, v62, v56
	v_fmac_f32_e32 v56, v107, v60
	v_div_scale_f32 v60, s[2:3], v57, v57, 1.0
	v_rcp_f32_e32 v61, v60
	s_nop 0
	v_fma_f32 v62, -v60, v61, 1.0
	v_fmac_f32_e32 v61, v62, v61
	v_div_scale_f32 v62, vcc, 1.0, v57, 1.0
	v_mul_f32_e32 v63, v62, v61
	v_fma_f32 v64, -v60, v63, v62
	v_fmac_f32_e32 v63, v64, v61
	v_fma_f32 v60, -v60, v63, v62
	v_div_fmas_f32 v60, v60, v61, v63
	v_div_fixup_f32 v57, v60, v57, 1.0
	v_div_scale_f32 v60, s[2:3], v55, v55, 1.0
	v_rcp_f32_e32 v61, v60
	v_mul_f32_e32 v57, 0xbf1b4598, v57
	v_mul_f32_e32 v57, 0x3fb8aa3b, v57
	v_exp_f32_e32 v57, v57
	v_fma_f32 v62, -v60, v61, 1.0
	v_fmac_f32_e32 v61, v62, v61
	v_div_scale_f32 v62, vcc, 1.0, v55, 1.0
	v_mul_f32_e32 v63, v62, v61
	v_fma_f32 v64, -v60, v63, v62
	v_fmac_f32_e32 v63, v64, v61
	v_fma_f32 v60, -v60, v63, v62
	v_div_fmas_f32 v60, v60, v61, v63
	v_div_fixup_f32 v55, v60, v55, 1.0
	v_mul_f32_e32 v60, v108, v54
	v_mul_f32_e32 v61, v60, v60
	s_nop 1
	v_mov_b32_dpp v61, v61 quad_perm:[1,0,3,2] row_mask:0xf bank_mask:0xf bound_ctrl:1
	v_fmac_f32_e32 v61, v60, v60
	s_nop 1
	v_add_f32_dpp v61, v61, v61 quad_perm:[2,3,0,1] row_mask:0xf bank_mask:0xf bound_ctrl:1
	s_nop 1
	v_add_f32_dpp v61, v61, v61 row_half_mirror row_mask:0xf bank_mask:0xf bound_ctrl:1
	s_nop 1
	v_add_f32_dpp v61, v61, v61 row_mirror row_mask:0xf bank_mask:0xf bound_ctrl:1
	s_nop 0
	v_readlane_b32 s3, v61, 16
	v_readlane_b32 s5, v61, 48
	v_readlane_b32 s2, v61, 0
	v_readlane_b32 s4, v61, 32
	v_mov_b32_e32 v61, s3
	v_mov_b32_e32 v62, s5
	v_add_f32_e32 v61, s2, v61
	v_add_f32_e32 v62, s4, v62
	v_add_f32_e32 v61, v61, v62
	v_max_f32_e32 v61, 0x179abe15, v61
	v_rsq_f32_e32 v61, v61
	s_movk_i32 s4, 0xff9
	v_mul_f32_e32 v60, v60, v61
	v_add_f32_e32 v61, -1.0, v55
	v_fma_f32 v61, v110, v61, 1.0
	v_mul_f32_e32 v61, v61, v54
	v_mul_f32_e32 v54, v43, v61
	v_mul_f32_e32 v62, v55, v60
	v_mul_f32_e32 v55, v104, v54
	v_cvt_pk_bf16_f32 v43, v43, s0
	s_nop 0
	v_mov_b32_dpp v55, v55 quad_perm:[1,0,3,2] row_mask:0xf bank_mask:0xf bound_ctrl:1
	v_fmac_f32_e32 v55, v104, v54
	s_nop 1
	v_add_f32_dpp v54, v55, v55 quad_perm:[2,3,0,1] row_mask:0xf bank_mask:0xf bound_ctrl:1
	s_nop 1
	v_add_f32_dpp v54, v54, v54 row_half_mirror row_mask:0xf bank_mask:0xf bound_ctrl:1
	s_nop 1
	v_add_f32_dpp v54, v54, v54 row_mirror row_mask:0xf bank_mask:0xf bound_ctrl:1
	s_nop 0
	v_readlane_b32 s2, v54, 0
	v_readlane_b32 s14, v54, 16
	v_readlane_b32 s3, v54, 32
	v_readlane_b32 s15, v54, 48
	v_and_or_b32 v54, v58, s4, v74
	v_mad_i64_i32 v[54:55], s[4:5], v54, s52, v[36:37]
	global_store_dword v[54:55], v57, off
	global_store_dword v[54:55], v60, off offset:256
	global_store_dword v[54:55], v62, off offset:512
	v_lshl_add_u64 v[54:55], v[54:55], 0, v[38:39]
	v_cvt_pk_bf16_f32 v57, v61, s0
	global_store_short v[54:55], v43, off offset:896
	v_cvt_pk_bf16_f32 v43, v56, s0
	global_store_short v[54:55], v57, off offset:768
	global_store_short v[54:55], v43, off offset:1024
	v_lshlrev_b64 v[54:55], 9, v[58:59]
	s_waitcnt lgkmcnt(6)
	v_cvt_pk_bf16_f32 v43, v118, s0
	v_lshl_add_u64 v[54:55], v[12:13], 0, v[54:55]
	global_store_short v[54:55], v43, off
	s_and_saveexec_b64 s[4:5], s[8:9]
	s_cbranch_execz .LBB0_1098
	v_mov_b32_e32 v56, s14
	v_mov_b32_e32 v57, s15
	v_pk_add_f32 v[56:57], s[2:3], v[56:57]
	v_lshl_add_u64 v[54:55], v[58:59], 4, v[14:15]
	v_add_f32_e32 v43, v56, v57
	global_store_dword v[54:55], v43, off
; DI u16 f2bf(float x) { return (u16)(pack2(x, 0.f) & 0xffffu); }
; DI float bf2f(u16 h) { return __uint_as_float(((unsigned)h) << 16); }
; DI float sigmoidf_(float x) { return 1.f / (1.f + __expf(-x)); }
; DI void phase_prep(const PRef& p, int l) {
;     ...
; #pragma unroll
;     for (int i = 0; i < 16; ++i) {
;       const int tok = tk0 + half * 16 + i;
;       const bool has_prev = (tok & (SEQ - 1)) != 0;
;       const u16* pr_ = rw + (size_t)tok * 896;
;       float r0 = bf2f(pr_[c]), k0 = bf2f(pr_[256 + c]), v0 = bf2f(pr_[512 + c]);
;       float r1 = 0.f, k1 = 0.f, v1 = 0.f;
;       if (has_prev) { r1 = bf2f(pr_[c - 896]); k1 = bf2f(pr_[256 + c - 896]); v1 = bf2f(pr_[512 + c - 896]); }
;       float r = r0 + (r1 - r0) * mur, k = k0 + (k1 - k0) * muk, v = v0 + (v1 - v0) * muv;
;       float w = __expf(-0.6065306597126334f * sigmoidf_(w0c + accw[i]));
;       float a = sigmoidf_(a0c + acca[i]);
;       float kk = k * kkc;
;       float ss = wave_sum(kk * kk);
;       kk *= rsqrtf(fmaxf(ss, 1e-24f));
;       float kp = k * (1.f + (a - 1.f) * kac);
;       float bb = kk * a;
;       float bo = wave_sum(r * kp * rkc);
;       const int b = tok >> 12, t = tok & (SEQ - 1);
;       char* rp = rec + ((size_t)((b * 4 + h) * SEQ + t)) * 1152;
;       const int cc = c & 63;
;       reinterpret_cast<float*>(rp)[cc] = w;
;       reinterpret_cast<float*>(rp + 256)[cc] = kk;
;       reinterpret_cast<float*>(rp + 512)[cc] = bb;
;       reinterpret_cast<u16*>(rp + 768)[cc] = f2bf(kp);
;       reinterpret_cast<u16*>(rp + 896)[cc] = f2bf(r);
;       reinterpret_cast<u16*>(rp + 1024)[cc] = f2bf(v);
;       gbuf[(size_t)tok * 256 + c] = f2bf(accg[i]);
;       if (cc == 0) bonus[(size_t)tok * 4 + h] = bo;
.LBB0_1098:
	s_or_b64 exec, exec, s[4:5]
	v_or_b32_e32 v54, 10, v42
	v_mad_i64_i32 v[56:57], s[2:3], v54, s79, v[34:35]
	v_add_f32_e32 v52, v52, v112
	v_mul_f32_e32 v52, 0xbfb8aa3b, v52
	v_exp_f32_e32 v52, v52
	v_add_f32_e32 v50, v50, v111
	v_mul_f32_e32 v50, 0xbfb8aa3b, v50
	v_exp_f32_e32 v50, v50
	v_add_f32_e32 v52, 1.0, v52
	v_ashrrev_i32_e32 v55, 31, v54
	v_add_f32_e32 v50, 1.0, v50
	v_lshlrev_b32_e32 v43, 16, v190
	v_lshlrev_b32_e32 v59, 16, v191
	v_lshlrev_b32_e32 v61, 16, v188
	v_lshlrev_b32_e32 v60, 16, v189
	v_lshlrev_b32_e32 v58, 16, v192
	v_lshlrev_b32_e32 v56, 16, v187
	v_sub_f32_e32 v56, v56, v43
	v_fmac_f32_e32 v43, v105, v56
	v_sub_f32_e32 v56, v61, v59
	v_fmac_f32_e32 v59, v106, v56
	v_sub_f32_e32 v56, v60, v58
	v_fmac_f32_e32 v58, v107, v56
	v_div_scale_f32 v56, s[2:3], v52, v52, 1.0
	v_rcp_f32_e32 v57, v56
	s_nop 0
	v_fma_f32 v60, -v56, v57, 1.0
	v_fmac_f32_e32 v57, v60, v57
	v_div_scale_f32 v60, vcc, 1.0, v52, 1.0
	v_mul_f32_e32 v61, v60, v57
	v_fma_f32 v62, -v56, v61, v60
	v_fmac_f32_e32 v61, v62, v57
	v_fma_f32 v56, -v56, v61, v60
	v_div_fmas_f32 v56, v56, v57, v61
	v_div_fixup_f32 v52, v56, v52, 1.0
	v_div_scale_f32 v56, s[2:3], v50, v50, 1.0
	v_rcp_f32_e32 v57, v56
	v_mul_f32_e32 v52, 0xbf1b4598, v52
	v_mul_f32_e32 v52, 0x3fb8aa3b, v52
	v_exp_f32_e32 v52, v52
	v_fma_f32 v60, -v56, v57, 1.0
	v_fmac_f32_e32 v57, v60, v57
	v_div_scale_f32 v60, vcc, 1.0, v50, 1.0
	v_mul_f32_e32 v61, v60, v57
	v_fma_f32 v62, -v56, v61, v60
	v_fmac_f32_e32 v61, v62, v57
	v_fma_f32 v56, -v56, v61, v60
	v_div_fmas_f32 v56, v56, v57, v61
	v_div_fixup_f32 v50, v56, v50, 1.0
	v_mul_f32_e32 v56, v108, v59
	v_mul_f32_e32 v57, v56, v56
	s_nop 1
	v_mov_b32_dpp v57, v57 quad_perm:[1,0,3,2] row_mask:0xf bank_mask:0xf bound_ctrl:1
	v_fmac_f32_e32 v57, v56, v56
	s_nop 1
	v_add_f32_dpp v57, v57, v57 quad_perm:[2,3,0,1] row_mask:0xf bank_mask:0xf bound_ctrl:1
	s_nop 1
	v_add_f32_dpp v57, v57, v57 row_half_mirror row_mask:0xf bank_mask:0xf bound_ctrl:1
	s_nop 1
	v_add_f32_dpp v57, v57, v57 row_mirror row_mask:0xf bank_mask:0xf bound_ctrl:1
	s_nop 0
	v_readlane_b32 s3, v57, 16
	v_readlane_b32 s5, v57, 48
	v_readlane_b32 s2, v57, 0
	v_readlane_b32 s4, v57, 32
	v_mov_b32_e32 v57, s3
	v_mov_b32_e32 v60, s5
	v_add_f32_e32 v57, s2, v57
	v_add_f32_e32 v60, s4, v60
	v_add_f32_e32 v57, v57, v60
	v_max_f32_e32 v57, 0x179abe15, v57
	v_rsq_f32_e32 v57, v57
	s_movk_i32 s4, 0xffa
	v_mul_f32_e32 v60, v56, v57
	v_add_f32_e32 v56, -1.0, v50
	v_fma_f32 v56, v110, v56, 1.0
	v_mul_f32_e32 v59, v56, v59
	v_mul_f32_e32 v56, v43, v59
	v_mul_f32_e32 v57, v104, v56
	v_mul_f32_e32 v50, v50, v60
	v_cvt_pk_bf16_f32 v43, v43, s0
	v_mov_b32_dpp v57, v57 quad_perm:[1,0,3,2] row_mask:0xf bank_mask:0xf bound_ctrl:1
	v_fmac_f32_e32 v57, v104, v56
	s_nop 1
	v_add_f32_dpp v56, v57, v57 quad_perm:[2,3,0,1] row_mask:0xf bank_mask:0xf bound_ctrl:1
	s_nop 1
	v_add_f32_dpp v56, v56, v56 row_half_mirror row_mask:0xf bank_mask:0xf bound_ctrl:1
	s_nop 1
	v_add_f32_dpp v56, v56, v56 row_mirror row_mask:0xf bank_mask:0xf bound_ctrl:1
	s_nop 0
	v_readlane_b32 s2, v56, 0
	v_readlane_b32 s14, v56, 16
	v_readlane_b32 s3, v56, 32
	v_readlane_b32 s15, v56, 48
	v_and_or_b32 v56, v54, s4, v74
	v_mad_i64_i32 v[56:57], s[4:5], v56, s52, v[36:37]
	global_store_dword v[56:57], v52, off
	global_store_dword v[56:57], v60, off offset:256
	global_store_dword v[56:57], v50, off offset:512
	v_lshl_add_u64 v[56:57], v[56:57], 0, v[38:39]
	v_cvt_pk_bf16_f32 v50, v59, s0
	global_store_short v[56:57], v43, off offset:896
	v_cvt_pk_bf16_f32 v43, v58, s0
	global_store_short v[56:57], v50, off offset:768
	global_store_short v[56:57], v43, off offset:1024
	v_lshlrev_b64 v[56:57], 9, v[54:55]
	s_waitcnt lgkmcnt(5)
	v_cvt_pk_bf16_f32 v43, v117, s0
	v_lshl_add_u64 v[56:57], v[12:13], 0, v[56:57]
	global_store_short v[56:57], v43, off
	s_and_saveexec_b64 s[4:5], s[8:9]
	s_cbranch_execz .LBB0_1100
	v_mov_b32_e32 v56, s14
	v_mov_b32_e32 v57, s15
	v_pk_add_f32 v[56:57], s[2:3], v[56:57]
	v_lshl_add_u64 v[54:55], v[54:55], 4, v[14:15]
	v_add_f32_e32 v43, v56, v57
	global_store_dword v[54:55], v43, off
.LBB0_1100:
	s_or_b64 exec, exec, s[4:5]
	v_or_b32_e32 v54, 11, v42
	v_mad_i64_i32 v[56:57], s[2:3], v54, s79, v[34:35]
	v_add_f32_e32 v53, v53, v112
	v_mul_f32_e32 v53, 0xbfb8aa3b, v53
	v_exp_f32_e32 v53, v53
	v_add_f32_e32 v51, v51, v111
	v_mul_f32_e32 v51, 0xbfb8aa3b, v51
	v_exp_f32_e32 v51, v51
	v_add_f32_e32 v53, 1.0, v53
	v_ashrrev_i32_e32 v55, 31, v54
	v_add_f32_e32 v51, 1.0, v51
	v_lshlrev_b32_e32 v43, 16, v193
	v_lshlrev_b32_e32 v50, 16, v194
	v_lshlrev_b32_e32 v52, 16, v195
	v_lshlrev_b32_e32 v58, 16, v192
	v_lshlrev_b32_e32 v59, 16, v191
	v_lshlrev_b32_e32 v56, 16, v190
	v_sub_f32_e32 v56, v56, v43
	v_fmac_f32_e32 v43, v105, v56
	v_sub_f32_e32 v56, v59, v50
	v_fmac_f32_e32 v50, v106, v56
	v_sub_f32_e32 v56, v58, v52
	v_fmac_f32_e32 v52, v107, v56
	v_div_scale_f32 v56, s[2:3], v53, v53, 1.0
	v_rcp_f32_e32 v57, v56
	s_nop 0
	v_fma_f32 v58, -v56, v57, 1.0
	v_fmac_f32_e32 v57, v58, v57
	v_div_scale_f32 v58, vcc, 1.0, v53, 1.0
	v_mul_f32_e32 v59, v58, v57
	v_fma_f32 v60, -v56, v59, v58
	v_fmac_f32_e32 v59, v60, v57
	v_fma_f32 v56, -v56, v59, v58
	v_div_fmas_f32 v56, v56, v57, v59
	v_div_fixup_f32 v53, v56, v53, 1.0
	v_div_scale_f32 v56, s[2:3], v51, v51, 1.0
	v_rcp_f32_e32 v57, v56
	v_mul_f32_e32 v53, 0xbf1b4598, v53
	v_mul_f32_e32 v53, 0x3fb8aa3b, v53
	v_exp_f32_e32 v53, v53
	v_fma_f32 v58, -v56, v57, 1.0
	v_fmac_f32_e32 v57, v58, v57
	v_div_scale_f32 v58, vcc, 1.0, v51, 1.0
	v_mul_f32_e32 v59, v58, v57
	v_fma_f32 v60, -v56, v59, v58
	v_fmac_f32_e32 v59, v60, v57
	v_fma_f32 v56, -v56, v59, v58
	v_div_fmas_f32 v56, v56, v57, v59
; DI u16 f2bf(float x) { return (u16)(pack2(x, 0.f) & 0xffffu); }
; DI float bf2f(u16 h) { return __uint_as_float(((unsigned)h) << 16); }
; DI float sigmoidf_(float x) { return 1.f / (1.f + __expf(-x)); }
; DI void phase_prep(const PRef& p, int l) {
;     ...
; #pragma unroll
;     for (int i = 0; i < 16; ++i) {
;       const int tok = tk0 + half * 16 + i;
;       const bool has_prev = (tok & (SEQ - 1)) != 0;
;       const u16* pr_ = rw + (size_t)tok * 896;
;       float r0 = bf2f(pr_[c]), k0 = bf2f(pr_[256 + c]), v0 = bf2f(pr_[512 + c]);
;       float r1 = 0.f, k1 = 0.f, v1 = 0.f;
;       if (has_prev) { r1 = bf2f(pr_[c - 896]); k1 = bf2f(pr_[256 + c - 896]); v1 = bf2f(pr_[512 + c - 896]); }
;       float r = r0 + (r1 - r0) * mur, k = k0 + (k1 - k0) * muk, v = v0 + (v1 - v0) * muv;
;       float w = __expf(-0.6065306597126334f * sigmoidf_(w0c + accw[i]));
;       float a = sigmoidf_(a0c + acca[i]);
;       float kk = k * kkc;
;       float ss = wave_sum(kk * kk);
;       kk *= rsqrtf(fmaxf(ss, 1e-24f));
;       float kp = k * (1.f + (a - 1.f) * kac);
;       float bb = kk * a;
;       float bo = wave_sum(r * kp * rkc);
;       const int b = tok >> 12, t = tok & (SEQ - 1);
;       char* rp = rec + ((size_t)((b * 4 + h) * SEQ + t)) * 1152;
;       const int cc = c & 63;
;       reinterpret_cast<float*>(rp)[cc] = w;
;       reinterpret_cast<float*>(rp + 256)[cc] = kk;
;       reinterpret_cast<float*>(rp + 512)[cc] = bb;
;       reinterpret_cast<u16*>(rp + 768)[cc] = f2bf(kp);
;       reinterpret_cast<u16*>(rp + 896)[cc] = f2bf(r);
;       reinterpret_cast<u16*>(rp + 1024)[cc] = f2bf(v);
;       gbuf[(size_t)tok * 256 + c] = f2bf(accg[i]);
;       if (cc == 0) bonus[(size_t)tok * 4 + h] = bo;
	v_div_fixup_f32 v51, v56, v51, 1.0
	v_mul_f32_e32 v56, v108, v50
	v_mul_f32_e32 v57, v56, v56
	s_nop 1
	v_mov_b32_dpp v57, v57 quad_perm:[1,0,3,2] row_mask:0xf bank_mask:0xf bound_ctrl:1
	v_fmac_f32_e32 v57, v56, v56
	s_nop 1
	v_add_f32_dpp v57, v57, v57 quad_perm:[2,3,0,1] row_mask:0xf bank_mask:0xf bound_ctrl:1
	s_nop 1
	v_add_f32_dpp v57, v57, v57 row_half_mirror row_mask:0xf bank_mask:0xf bound_ctrl:1
	s_nop 1
	v_add_f32_dpp v57, v57, v57 row_mirror row_mask:0xf bank_mask:0xf bound_ctrl:1
	s_nop 0
	v_readlane_b32 s3, v57, 16
	v_readlane_b32 s5, v57, 48
	v_readlane_b32 s2, v57, 0
	v_readlane_b32 s4, v57, 32
	v_mov_b32_e32 v57, s3
	v_mov_b32_e32 v58, s5
	v_add_f32_e32 v57, s2, v57
	v_add_f32_e32 v58, s4, v58
	v_add_f32_e32 v57, v57, v58
	v_max_f32_e32 v57, 0x179abe15, v57
	v_rsq_f32_e32 v57, v57
	s_movk_i32 s4, 0xffb
	v_mul_f32_e32 v56, v56, v57
	v_add_f32_e32 v57, -1.0, v51
	v_fma_f32 v57, v110, v57, 1.0
	v_mul_f32_e32 v57, v57, v50
	v_mul_f32_e32 v50, v43, v57
	v_mul_f32_e32 v58, v51, v56
	v_mul_f32_e32 v51, v104, v50
	v_cvt_pk_bf16_f32 v43, v43, s0
	s_nop 0
	v_mov_b32_dpp v51, v51 quad_perm:[1,0,3,2] row_mask:0xf bank_mask:0xf bound_ctrl:1
	v_fmac_f32_e32 v51, v104, v50
	s_nop 1
	v_add_f32_dpp v50, v51, v51 quad_perm:[2,3,0,1] row_mask:0xf bank_mask:0xf bound_ctrl:1
	s_nop 1
	v_add_f32_dpp v50, v50, v50 row_half_mirror row_mask:0xf bank_mask:0xf bound_ctrl:1
	s_nop 1
	v_add_f32_dpp v50, v50, v50 row_mirror row_mask:0xf bank_mask:0xf bound_ctrl:1
	s_nop 0
	v_readlane_b32 s2, v50, 0
	v_readlane_b32 s14, v50, 16
	v_readlane_b32 s3, v50, 32
	v_readlane_b32 s15, v50, 48
	v_and_or_b32 v50, v54, s4, v74
	v_mad_i64_i32 v[50:51], s[4:5], v50, s52, v[36:37]
	global_store_dword v[50:51], v53, off
	global_store_dword v[50:51], v56, off offset:256
	global_store_dword v[50:51], v58, off offset:512
	v_lshl_add_u64 v[50:51], v[50:51], 0, v[38:39]
	v_cvt_pk_bf16_f32 v53, v57, s0
	global_store_short v[50:51], v43, off offset:896
	v_cvt_pk_bf16_f32 v43, v52, s0
	global_store_short v[50:51], v53, off offset:768
	global_store_short v[50:51], v43, off offset:1024
	v_lshlrev_b64 v[50:51], 9, v[54:55]
	s_waitcnt lgkmcnt(4)
	v_cvt_pk_bf16_f32 v43, v116, s0
	v_lshl_add_u64 v[50:51], v[12:13], 0, v[50:51]
	global_store_short v[50:51], v43, off
	s_and_saveexec_b64 s[4:5], s[8:9]
	s_cbranch_execz .LBB0_1102
	v_mov_b32_e32 v52, s14
	v_mov_b32_e32 v53, s15
	v_pk_add_f32 v[52:53], s[2:3], v[52:53]
	v_lshl_add_u64 v[50:51], v[54:55], 4, v[14:15]
	v_add_f32_e32 v43, v52, v53
	global_store_dword v[50:51], v43, off
.LBB0_1102:
	s_or_b64 exec, exec, s[4:5]
	v_or_b32_e32 v50, 12, v42
	v_mad_i64_i32 v[52:53], s[2:3], v50, s79, v[34:35]
	v_add_f32_e32 v48, v48, v112
	v_mul_f32_e32 v48, 0xbfb8aa3b, v48
	v_exp_f32_e32 v48, v48
	s_movk_i32 s2, 0xffc
	v_and_or_b32 v52, v50, s2, v74
	v_add_f32_e32 v46, v46, v111
	v_add_f32_e32 v48, 1.0, v48
	v_div_scale_f32 v61, s[2:3], v48, v48, 1.0
	v_rcp_f32_e32 v64, v61
	v_mul_f32_e32 v46, 0xbfb8aa3b, v46
	v_exp_f32_e32 v46, v46
	v_div_scale_f32 v62, vcc, 1.0, v48, 1.0
	v_fma_f32 v67, -v61, v64, 1.0
	v_fmac_f32_e32 v64, v67, v64
	v_mul_f32_e32 v67, v62, v64
	v_fma_f32 v69, -v61, v67, v62
	v_fmac_f32_e32 v67, v69, v64
	v_add_f32_e32 v46, 1.0, v46
	v_fma_f32 v61, -v61, v67, v62
	v_div_scale_f32 v63, s[2:3], v46, v46, 1.0
	v_div_fmas_f32 v61, v61, v64, v67
	v_rcp_f32_e32 v65, v63
	v_div_fixup_f32 v48, v61, v48, 1.0
	v_mul_f32_e32 v48, 0xbf1b4598, v48
	v_mul_f32_e32 v48, 0x3fb8aa3b, v48
	v_exp_f32_e32 v48, v48
	v_fma_f32 v68, -v63, v65, 1.0
	v_div_scale_f32 v66, s[14:15], 1.0, v46, 1.0
	v_fmac_f32_e32 v65, v68, v65
	v_mad_i64_i32 v[54:55], s[2:3], v52, s52, v[36:37]
	v_mul_f32_e32 v68, v66, v65
	v_fma_f32 v70, -v63, v68, v66
	global_store_dword v[54:55], v48, off
	v_fmac_f32_e32 v68, v70, v65
	v_fma_f32 v62, -v63, v68, v66
	s_mov_b64 vcc, s[14:15]
	v_div_fmas_f32 v61, v62, v65, v68
	v_div_fixup_f32 v46, v61, v46, 1.0
	v_add_f32_e32 v61, -1.0, v46
	v_fma_f32 v61, v110, v61, 1.0
	v_lshl_add_u64 v[52:53], v[54:55], 0, v[38:39]
	v_ashrrev_i32_e32 v51, 31, v50
	v_lshlrev_b32_e32 v43, 16, v196
	v_lshlrev_b32_e32 v48, 16, v197
	v_lshlrev_b32_e32 v56, 16, v198
	v_lshlrev_b32_e32 v57, 16, v195
	v_lshlrev_b32_e32 v58, 16, v194
	v_sub_f32_e32 v58, v58, v48
	v_sub_f32_e32 v57, v57, v56
	v_fmac_f32_e32 v48, v106, v58
	v_fmac_f32_e32 v56, v107, v57
	v_mul_f32_e32 v57, v108, v48
	v_mul_f32_e32 v58, v57, v57
	v_lshlrev_b32_e32 v59, 16, v193
	v_sub_f32_e32 v59, v59, v43
	v_mov_b32_dpp v58, v58 quad_perm:[1,0,3,2] row_mask:0xf bank_mask:0xf bound_ctrl:1
	v_fmac_f32_e32 v58, v57, v57
	v_fmac_f32_e32 v43, v105, v59
	v_mul_f32_e32 v48, v61, v48
	v_add_f32_dpp v58, v58, v58 quad_perm:[2,3,0,1] row_mask:0xf bank_mask:0xf bound_ctrl:1
	v_mul_f32_e32 v59, v43, v48
	v_cvt_pk_bf16_f32 v48, v48, s0
	v_add_f32_dpp v58, v58, v58 row_half_mirror row_mask:0xf bank_mask:0xf bound_ctrl:1
	v_mul_f32_e32 v60, v104, v59
	global_store_short v[52:53], v48, off offset:768
	v_add_f32_dpp v58, v58, v58 row_mirror row_mask:0xf bank_mask:0xf bound_ctrl:1
	v_mov_b32_dpp v48, v60 quad_perm:[1,0,3,2] row_mask:0xf bank_mask:0xf bound_ctrl:1
	v_readlane_b32 s2, v58, 16
	v_readlane_b32 s5, v58, 48
	v_fmac_f32_e32 v48, v104, v59
	v_readlane_b32 s3, v58, 0
	v_readlane_b32 s4, v58, 32
	v_mov_b32_e32 v58, s2
	v_mov_b32_e32 v59, s5
	v_add_f32_e32 v58, s3, v58
	v_add_f32_e32 v59, s4, v59
	v_add_f32_e32 v58, v58, v59
	v_max_f32_e32 v58, 0x179abe15, v58
	v_rsq_f32_e32 v58, v58
	v_add_f32_dpp v48, v48, v48 quad_perm:[2,3,0,1] row_mask:0xf bank_mask:0xf bound_ctrl:1
	v_cvt_pk_bf16_f32 v43, v43, s0
	s_nop 0
	v_add_f32_dpp v48, v48, v48 row_half_mirror row_mask:0xf bank_mask:0xf bound_ctrl:1
	s_nop 1
	v_add_f32_dpp v48, v48, v48 row_mirror row_mask:0xf bank_mask:0xf bound_ctrl:1
	s_nop 0
	v_readlane_b32 s2, v48, 0
	v_readlane_b32 s14, v48, 16
	v_readlane_b32 s3, v48, 32
	v_readlane_b32 s15, v48, 48
	v_mul_f32_e32 v48, v57, v58
	v_mul_f32_e32 v46, v46, v48
	global_store_dword v[54:55], v48, off offset:256
	global_store_dword v[54:55], v46, off offset:512
	global_store_short v[52:53], v43, off offset:896
	v_cvt_pk_bf16_f32 v43, v56, s0
	global_store_short v[52:53], v43, off offset:1024
	v_lshlrev_b64 v[52:53], 9, v[50:51]
	s_waitcnt lgkmcnt(3)
	v_cvt_pk_bf16_f32 v43, v115, s0
	v_lshl_add_u64 v[52:53], v[12:13], 0, v[52:53]
	global_store_short v[52:53], v43, off
	s_and_saveexec_b64 s[4:5], s[8:9]
	s_cbranch_execz .LBB0_1104
	v_mov_b32_e32 v52, s14
	v_mov_b32_e32 v53, s15
	v_pk_add_f32 v[52:53], s[2:3], v[52:53]
	v_lshl_add_u64 v[50:51], v[50:51], 4, v[14:15]
	v_add_f32_e32 v43, v52, v53
	global_store_dword v[50:51], v43, off
; DI u16 f2bf(float x) { return (u16)(pack2(x, 0.f) & 0xffffu); }
; DI float bf2f(u16 h) { return __uint_as_float(((unsigned)h) << 16); }
; DI float sigmoidf_(float x) { return 1.f / (1.f + __expf(-x)); }
; DI void phase_prep(const PRef& p, int l) {
;     ...
; #pragma unroll
;     for (int i = 0; i < 16; ++i) {
;       const int tok = tk0 + half * 16 + i;
;       const bool has_prev = (tok & (SEQ - 1)) != 0;
;       const u16* pr_ = rw + (size_t)tok * 896;
;       float r0 = bf2f(pr_[c]), k0 = bf2f(pr_[256 + c]), v0 = bf2f(pr_[512 + c]);
;       float r1 = 0.f, k1 = 0.f, v1 = 0.f;
;       if (has_prev) { r1 = bf2f(pr_[c - 896]); k1 = bf2f(pr_[256 + c - 896]); v1 = bf2f(pr_[512 + c - 896]); }
;       float r = r0 + (r1 - r0) * mur, k = k0 + (k1 - k0) * muk, v = v0 + (v1 - v0) * muv;
;       float w = __expf(-0.6065306597126334f * sigmoidf_(w0c + accw[i]));
;       float a = sigmoidf_(a0c + acca[i]);
;       float kk = k * kkc;
;       float ss = wave_sum(kk * kk);
;       kk *= rsqrtf(fmaxf(ss, 1e-24f));
;       float kp = k * (1.f + (a - 1.f) * kac);
;       float bb = kk * a;
;       float bo = wave_sum(r * kp * rkc);
;       const int b = tok >> 12, t = tok & (SEQ - 1);
;       char* rp = rec + ((size_t)((b * 4 + h) * SEQ + t)) * 1152;
;       const int cc = c & 63;
;       reinterpret_cast<float*>(rp)[cc] = w;
;       reinterpret_cast<float*>(rp + 256)[cc] = kk;
;       reinterpret_cast<float*>(rp + 512)[cc] = bb;
;       reinterpret_cast<u16*>(rp + 768)[cc] = f2bf(kp);
;       reinterpret_cast<u16*>(rp + 896)[cc] = f2bf(r);
;       reinterpret_cast<u16*>(rp + 1024)[cc] = f2bf(v);
;       gbuf[(size_t)tok * 256 + c] = f2bf(accg[i]);
;       if (cc == 0) bonus[(size_t)tok * 4 + h] = bo;
.LBB0_1104:
	s_or_b64 exec, exec, s[4:5]
	v_or_b32_e32 v46, 13, v42
	v_mad_i64_i32 v[50:51], s[2:3], v46, s79, v[34:35]
	v_add_f32_e32 v48, v49, v112
	v_mul_f32_e32 v48, 0xbfb8aa3b, v48
	v_add_f32_e32 v49, v47, v111
	v_exp_f32_e32 v57, v48
	v_mul_f32_e32 v49, 0xbfb8aa3b, v49
	v_exp_f32_e32 v58, v49
	s_movk_i32 s2, 0xffd
	v_add_f32_e32 v57, 1.0, v57
	v_and_or_b32 v50, v46, s2, v74
	v_div_scale_f32 v59, s[2:3], v57, v57, 1.0
	v_add_f32_e32 v58, 1.0, v58
	v_rcp_f32_e32 v62, v59
	v_div_scale_f32 v61, s[2:3], v58, v58, 1.0
	v_rcp_f32_e32 v63, v61
	v_fma_f32 v65, -v59, v62, 1.0
	v_div_scale_f32 v60, vcc, 1.0, v57, 1.0
	v_fmac_f32_e32 v62, v65, v62
	v_fma_f32 v66, -v61, v63, 1.0
	v_mul_f32_e32 v65, v60, v62
	v_div_scale_f32 v64, s[14:15], 1.0, v58, 1.0
	v_fmac_f32_e32 v63, v66, v63
	v_fma_f32 v67, -v59, v65, v60
	v_mul_f32_e32 v66, v64, v63
	v_fmac_f32_e32 v65, v67, v62
	v_fma_f32 v68, -v61, v66, v64
	v_fma_f32 v59, -v59, v65, v60
	v_fmac_f32_e32 v66, v68, v63
	v_div_fmas_f32 v59, v59, v62, v65
	v_fma_f32 v60, -v61, v66, v64
	v_div_fixup_f32 v57, v59, v57, 1.0
	s_mov_b64 vcc, s[14:15]
	v_div_fmas_f32 v59, v60, v63, v66
	v_mul_f32_e32 v57, 0xbf1b4598, v57
	v_mul_f32_e32 v57, 0x3fb8aa3b, v57
	v_div_fixup_f32 v58, v59, v58, 1.0
	v_exp_f32_e32 v57, v57
	v_add_f32_e32 v59, -1.0, v58
	v_fma_f32 v59, v110, v59, 1.0
	v_mad_i64_i32 v[48:49], s[2:3], v50, s52, v[36:37]
	v_lshl_add_u64 v[50:51], v[48:49], 0, v[38:39]
	global_store_dword v[48:49], v57, off
	v_ashrrev_i32_e32 v47, 31, v46
	v_lshlrev_b32_e32 v43, 16, v199
	v_lshlrev_b32_e32 v52, 16, v200
	v_lshlrev_b32_e32 v53, 16, v201
	v_lshlrev_b32_e32 v54, 16, v198
	v_lshlrev_b32_e32 v55, 16, v197
	v_sub_f32_e32 v55, v55, v52
	v_sub_f32_e32 v54, v54, v53
	v_fmac_f32_e32 v52, v106, v55
	v_fmac_f32_e32 v53, v107, v54
	v_mul_f32_e32 v54, v108, v52
	v_mul_f32_e32 v55, v54, v54
	v_lshlrev_b32_e32 v56, 16, v196
	v_sub_f32_e32 v56, v56, v43
	v_mov_b32_dpp v55, v55 quad_perm:[1,0,3,2] row_mask:0xf bank_mask:0xf bound_ctrl:1
	v_fmac_f32_e32 v55, v54, v54
	v_fmac_f32_e32 v43, v105, v56
	v_mul_f32_e32 v52, v59, v52
	v_add_f32_dpp v55, v55, v55 quad_perm:[2,3,0,1] row_mask:0xf bank_mask:0xf bound_ctrl:1
	v_mul_f32_e32 v56, v43, v52
	v_cvt_pk_bf16_f32 v52, v52, s0
	v_add_f32_dpp v55, v55, v55 row_half_mirror row_mask:0xf bank_mask:0xf bound_ctrl:1
	v_mul_f32_e32 v57, v104, v56
	global_store_short v[50:51], v52, off offset:768
	v_add_f32_dpp v55, v55, v55 row_mirror row_mask:0xf bank_mask:0xf bound_ctrl:1
	v_mov_b32_dpp v52, v57 quad_perm:[1,0,3,2] row_mask:0xf bank_mask:0xf bound_ctrl:1
	v_readlane_b32 s2, v55, 16
	v_readlane_b32 s5, v55, 48
	v_fmac_f32_e32 v52, v104, v56
	v_readlane_b32 s3, v55, 0
	v_readlane_b32 s4, v55, 32
	v_mov_b32_e32 v55, s2
	v_mov_b32_e32 v56, s5
	v_add_f32_e32 v55, s3, v55
	v_add_f32_e32 v56, s4, v56
	v_add_f32_e32 v55, v55, v56
	v_max_f32_e32 v55, 0x179abe15, v55
	v_rsq_f32_e32 v55, v55
	v_add_f32_dpp v52, v52, v52 quad_perm:[2,3,0,1] row_mask:0xf bank_mask:0xf bound_ctrl:1
	v_cvt_pk_bf16_f32 v43, v43, s0
	s_nop 0
	v_add_f32_dpp v52, v52, v52 row_half_mirror row_mask:0xf bank_mask:0xf bound_ctrl:1
	s_nop 1
	v_add_f32_dpp v52, v52, v52 row_mirror row_mask:0xf bank_mask:0xf bound_ctrl:1
	s_nop 0
	v_readlane_b32 s2, v52, 0
	v_readlane_b32 s14, v52, 16
	v_readlane_b32 s3, v52, 32
	v_readlane_b32 s15, v52, 48
	v_mul_f32_e32 v52, v54, v55
	v_mul_f32_e32 v54, v58, v52
	global_store_dword v[48:49], v52, off offset:256
	global_store_dword v[48:49], v54, off offset:512
	global_store_short v[50:51], v43, off offset:896
	v_cvt_pk_bf16_f32 v43, v53, s0
	v_lshlrev_b64 v[48:49], 9, v[46:47]
	global_store_short v[50:51], v43, off offset:1024
	s_waitcnt lgkmcnt(2)
	v_cvt_pk_bf16_f32 v43, v114, s0
	v_lshl_add_u64 v[48:49], v[12:13], 0, v[48:49]
	global_store_short v[48:49], v43, off
	s_and_saveexec_b64 s[4:5], s[8:9]
	s_cbranch_execz .LBB0_1106
	v_mov_b32_e32 v48, s14
	v_mov_b32_e32 v49, s15
	v_pk_add_f32 v[48:49], s[2:3], v[48:49]
	v_lshl_add_u64 v[46:47], v[46:47], 4, v[14:15]
	v_add_f32_e32 v43, v48, v49
	global_store_dword v[46:47], v43, off
.LBB0_1106:
	s_or_b64 exec, exec, s[4:5]
	v_or_b32_e32 v46, 14, v42
	v_mad_i64_i32 v[48:49], s[2:3], v46, s79, v[34:35]
	v_add_f32_e32 v44, v44, v112
	v_mul_f32_e32 v44, 0xbfb8aa3b, v44
	v_exp_f32_e32 v44, v44
	s_movk_i32 s2, 0xffe
	v_and_or_b32 v48, v46, s2, v74
	v_add_f32_e32 v40, v40, v111
	v_add_f32_e32 v44, 1.0, v44
	v_div_scale_f32 v57, s[2:3], v44, v44, 1.0
	v_rcp_f32_e32 v60, v57
	v_mul_f32_e32 v40, 0xbfb8aa3b, v40
	v_exp_f32_e32 v40, v40
	v_div_scale_f32 v58, vcc, 1.0, v44, 1.0
	v_fma_f32 v63, -v57, v60, 1.0
	v_fmac_f32_e32 v60, v63, v60
	v_mul_f32_e32 v63, v58, v60
	v_fma_f32 v65, -v57, v63, v58
	v_fmac_f32_e32 v63, v65, v60
	v_add_f32_e32 v40, 1.0, v40
	v_fma_f32 v57, -v57, v63, v58
	v_div_scale_f32 v59, s[2:3], v40, v40, 1.0
	v_div_fmas_f32 v57, v57, v60, v63
	v_rcp_f32_e32 v61, v59
	v_div_fixup_f32 v44, v57, v44, 1.0
	v_mul_f32_e32 v44, 0xbf1b4598, v44
	v_mul_f32_e32 v44, 0x3fb8aa3b, v44
	v_exp_f32_e32 v44, v44
	v_fma_f32 v64, -v59, v61, 1.0
	v_div_scale_f32 v62, s[14:15], 1.0, v40, 1.0
	v_fmac_f32_e32 v61, v64, v61
	v_mad_i64_i32 v[48:49], s[2:3], v48, s52, v[36:37]
	v_mul_f32_e32 v64, v62, v61
	v_fma_f32 v66, -v59, v64, v62
	global_store_dword v[48:49], v44, off
	v_fmac_f32_e32 v64, v66, v61
	v_fma_f32 v58, -v59, v64, v62
	s_mov_b64 vcc, s[14:15]
	v_div_fmas_f32 v57, v58, v61, v64
	v_div_fixup_f32 v40, v57, v40, 1.0
	v_add_f32_e32 v57, -1.0, v40
	v_fma_f32 v57, v110, v57, 1.0
	v_lshl_add_u64 v[50:51], v[48:49], 0, v[38:39]
	v_ashrrev_i32_e32 v47, 31, v46
	v_lshlrev_b32_e32 v43, 16, v202
	v_lshlrev_b32_e32 v44, 16, v203
	v_lshlrev_b32_e32 v52, 16, v204
; DI u16 f2bf(float x) { return (u16)(pack2(x, 0.f) & 0xffffu); }
; DI float bf2f(u16 h) { return __uint_as_float(((unsigned)h) << 16); }
; DI float sigmoidf_(float x) { return 1.f / (1.f + __expf(-x)); }
; DI void phase_prep(const PRef& p, int l) {
;     ...
; #pragma unroll
;     for (int i = 0; i < 16; ++i) {
;       const int tok = tk0 + half * 16 + i;
;       const bool has_prev = (tok & (SEQ - 1)) != 0;
;       const u16* pr_ = rw + (size_t)tok * 896;
;       float r0 = bf2f(pr_[c]), k0 = bf2f(pr_[256 + c]), v0 = bf2f(pr_[512 + c]);
;       float r1 = 0.f, k1 = 0.f, v1 = 0.f;
;       if (has_prev) { r1 = bf2f(pr_[c - 896]); k1 = bf2f(pr_[256 + c - 896]); v1 = bf2f(pr_[512 + c - 896]); }
;       float r = r0 + (r1 - r0) * mur, k = k0 + (k1 - k0) * muk, v = v0 + (v1 - v0) * muv;
;       float w = __expf(-0.6065306597126334f * sigmoidf_(w0c + accw[i]));
;       float a = sigmoidf_(a0c + acca[i]);
;       float kk = k * kkc;
;       float ss = wave_sum(kk * kk);
;       kk *= rsqrtf(fmaxf(ss, 1e-24f));
;       float kp = k * (1.f + (a - 1.f) * kac);
;       float bb = kk * a;
;       float bo = wave_sum(r * kp * rkc);
;       const int b = tok >> 12, t = tok & (SEQ - 1);
;       char* rp = rec + ((size_t)((b * 4 + h) * SEQ + t)) * 1152;
;       const int cc = c & 63;
;       reinterpret_cast<float*>(rp)[cc] = w;
;       reinterpret_cast<float*>(rp + 256)[cc] = kk;
;       reinterpret_cast<float*>(rp + 512)[cc] = bb;
;       reinterpret_cast<u16*>(rp + 768)[cc] = f2bf(kp);
;       reinterpret_cast<u16*>(rp + 896)[cc] = f2bf(r);
;       reinterpret_cast<u16*>(rp + 1024)[cc] = f2bf(v);
;       gbuf[(size_t)tok * 256 + c] = f2bf(accg[i]);
;       if (cc == 0) bonus[(size_t)tok * 4 + h] = bo;
;     }
	v_lshlrev_b32_e32 v53, 16, v201
	v_lshlrev_b32_e32 v54, 16, v200
	v_sub_f32_e32 v54, v54, v44
	v_sub_f32_e32 v53, v53, v52
	v_fmac_f32_e32 v44, v106, v54
	v_fmac_f32_e32 v52, v107, v53
	v_mul_f32_e32 v53, v108, v44
	v_mul_f32_e32 v54, v53, v53
	v_lshlrev_b32_e32 v55, 16, v199
	v_sub_f32_e32 v55, v55, v43
	v_mov_b32_dpp v54, v54 quad_perm:[1,0,3,2] row_mask:0xf bank_mask:0xf bound_ctrl:1
	v_fmac_f32_e32 v54, v53, v53
	v_fmac_f32_e32 v43, v105, v55
	v_mul_f32_e32 v44, v57, v44
	v_add_f32_dpp v54, v54, v54 quad_perm:[2,3,0,1] row_mask:0xf bank_mask:0xf bound_ctrl:1
	v_mul_f32_e32 v55, v43, v44
	v_cvt_pk_bf16_f32 v44, v44, s0
	v_add_f32_dpp v54, v54, v54 row_half_mirror row_mask:0xf bank_mask:0xf bound_ctrl:1
	v_mul_f32_e32 v56, v104, v55
	global_store_short v[50:51], v44, off offset:768
	v_add_f32_dpp v54, v54, v54 row_mirror row_mask:0xf bank_mask:0xf bound_ctrl:1
	v_mov_b32_dpp v44, v56 quad_perm:[1,0,3,2] row_mask:0xf bank_mask:0xf bound_ctrl:1
	v_readlane_b32 s2, v54, 16
	v_readlane_b32 s5, v54, 48
	v_fmac_f32_e32 v44, v104, v55
	v_readlane_b32 s3, v54, 0
	v_readlane_b32 s4, v54, 32
	v_mov_b32_e32 v54, s2
	v_mov_b32_e32 v55, s5
	v_add_f32_e32 v54, s3, v54
	v_add_f32_e32 v55, s4, v55
	v_add_f32_e32 v54, v54, v55
	v_max_f32_e32 v54, 0x179abe15, v54
	v_rsq_f32_e32 v54, v54
	v_add_f32_dpp v44, v44, v44 quad_perm:[2,3,0,1] row_mask:0xf bank_mask:0xf bound_ctrl:1
	s_nop 1
	v_add_f32_dpp v44, v44, v44 row_half_mirror row_mask:0xf bank_mask:0xf bound_ctrl:1
	s_nop 1
	v_add_f32_dpp v44, v44, v44 row_mirror row_mask:0xf bank_mask:0xf bound_ctrl:1
	s_nop 0
	v_readlane_b32 s2, v44, 0
	v_readlane_b32 s14, v44, 16
	v_readlane_b32 s3, v44, 32
	v_readlane_b32 s15, v44, 48
	v_mul_f32_e32 v44, v53, v54
	v_mul_f32_e32 v40, v40, v44
	global_store_dword v[48:49], v44, off offset:256
	global_store_dword v[48:49], v40, off offset:512
	v_cvt_pk_bf16_f32 v40, v43, s0
	global_store_short v[50:51], v40, off offset:896
	v_cvt_pk_bf16_f32 v40, v52, s0
	v_lshlrev_b64 v[48:49], 9, v[46:47]
	global_store_short v[50:51], v40, off offset:1024
	s_waitcnt lgkmcnt(1)
	v_cvt_pk_bf16_f32 v40, v113, s0
	v_lshl_add_u64 v[48:49], v[12:13], 0, v[48:49]
	global_store_short v[48:49], v40, off
	s_and_saveexec_b64 s[4:5], s[8:9]
	s_cbranch_execz .LBB0_1108
	v_mov_b32_e32 v48, s14
	v_mov_b32_e32 v49, s15
	v_pk_add_f32 v[48:49], s[2:3], v[48:49]
	v_lshl_add_u64 v[46:47], v[46:47], 4, v[14:15]
	v_add_f32_e32 v40, v48, v49
	global_store_dword v[46:47], v40, off
.LBB0_1108:
	s_or_b64 exec, exec, s[4:5]
	v_or_b32_e32 v40, 15, v42
	v_mad_i64_i32 v[42:43], s[2:3], v40, s79, v[34:35]
	v_add_f32_e32 v42, v45, v112
	v_mul_f32_e32 v42, 0xbfb8aa3b, v42
	v_add_f32_e32 v43, v41, v111
	v_exp_f32_e32 v52, v42
	v_mul_f32_e32 v43, 0xbfb8aa3b, v43
	v_exp_f32_e32 v53, v43
	v_and_or_b32 v44, v40, s48, v74
	v_add_f32_e32 v52, 1.0, v52
	v_div_scale_f32 v54, s[2:3], v52, v52, 1.0
	v_add_f32_e32 v53, 1.0, v53
	v_rcp_f32_e32 v57, v54
	v_div_scale_f32 v56, s[2:3], v53, v53, 1.0
	v_rcp_f32_e32 v58, v56
	v_fma_f32 v60, -v54, v57, 1.0
	v_div_scale_f32 v55, vcc, 1.0, v52, 1.0
	v_fmac_f32_e32 v57, v60, v57
	v_fma_f32 v61, -v56, v58, 1.0
	v_mul_f32_e32 v60, v55, v57
	v_div_scale_f32 v59, s[14:15], 1.0, v53, 1.0
	v_fmac_f32_e32 v58, v61, v58
	v_fma_f32 v62, -v54, v60, v55
	v_mul_f32_e32 v61, v59, v58
	v_fmac_f32_e32 v60, v62, v57
	v_fma_f32 v63, -v56, v61, v59
	v_fma_f32 v54, -v54, v60, v55
	v_fmac_f32_e32 v61, v63, v58
	v_div_fmas_f32 v54, v54, v57, v60
	v_fma_f32 v55, -v56, v61, v59
	v_div_fixup_f32 v52, v54, v52, 1.0
	s_mov_b64 vcc, s[14:15]
	v_div_fmas_f32 v54, v55, v58, v61
	v_mul_f32_e32 v52, 0xbf1b4598, v52
	v_mul_f32_e32 v52, 0x3fb8aa3b, v52
	v_div_fixup_f32 v53, v54, v53, 1.0
	v_exp_f32_e32 v52, v52
	v_add_f32_e32 v54, -1.0, v53
	v_fma_f32 v54, v110, v54, 1.0
	v_mad_i64_i32 v[42:43], s[2:3], v44, s52, v[36:37]
	v_lshl_add_u64 v[44:45], v[42:43], 0, v[38:39]
	global_store_dword v[42:43], v52, off
	v_ashrrev_i32_e32 v41, 31, v40
	v_lshlrev_b32_e32 v46, 16, v205
	v_lshlrev_b32_e32 v47, 16, v206
	v_lshlrev_b32_e32 v48, 16, v207
	v_lshlrev_b32_e32 v49, 16, v204
	v_lshlrev_b32_e32 v50, 16, v203
	v_sub_f32_e32 v50, v50, v47
	v_sub_f32_e32 v49, v49, v48
	v_fmac_f32_e32 v47, v106, v50
	v_fmac_f32_e32 v48, v107, v49
	v_mul_f32_e32 v49, v108, v47
	v_mul_f32_e32 v50, v49, v49
	v_lshlrev_b32_e32 v51, 16, v202
	v_sub_f32_e32 v51, v51, v46
	v_mov_b32_dpp v50, v50 quad_perm:[1,0,3,2] row_mask:0xf bank_mask:0xf bound_ctrl:1
	v_fmac_f32_e32 v50, v49, v49
	v_fmac_f32_e32 v46, v105, v51
	v_mul_f32_e32 v47, v54, v47
	v_add_f32_dpp v50, v50, v50 quad_perm:[2,3,0,1] row_mask:0xf bank_mask:0xf bound_ctrl:1
	v_mul_f32_e32 v51, v46, v47
	v_cvt_pk_bf16_f32 v47, v47, s0
	v_add_f32_dpp v50, v50, v50 row_half_mirror row_mask:0xf bank_mask:0xf bound_ctrl:1
	v_mul_f32_e32 v52, v104, v51
	global_store_short v[44:45], v47, off offset:768
	v_add_f32_dpp v50, v50, v50 row_mirror row_mask:0xf bank_mask:0xf bound_ctrl:1
	v_mov_b32_dpp v47, v52 quad_perm:[1,0,3,2] row_mask:0xf bank_mask:0xf bound_ctrl:1
	v_readlane_b32 s2, v50, 16
	v_readlane_b32 s5, v50, 48
	v_fmac_f32_e32 v47, v104, v51
	v_readlane_b32 s3, v50, 0
	v_readlane_b32 s4, v50, 32
	v_mov_b32_e32 v50, s2
	v_mov_b32_e32 v51, s5
	v_add_f32_e32 v50, s3, v50
	v_add_f32_e32 v51, s4, v51
	v_add_f32_e32 v50, v50, v51
	v_max_f32_e32 v50, 0x179abe15, v50
	v_rsq_f32_e32 v50, v50
	v_add_f32_dpp v47, v47, v47 quad_perm:[2,3,0,1] row_mask:0xf bank_mask:0xf bound_ctrl:1
	s_nop 1
	v_add_f32_dpp v47, v47, v47 row_half_mirror row_mask:0xf bank_mask:0xf bound_ctrl:1
	s_nop 1
	v_add_f32_dpp v47, v47, v47 row_mirror row_mask:0xf bank_mask:0xf bound_ctrl:1
	s_nop 0
	v_readlane_b32 s2, v47, 0
	v_readlane_b32 s14, v47, 16
	v_readlane_b32 s3, v47, 32
	v_readlane_b32 s15, v47, 48
	v_mul_f32_e32 v47, v49, v50
	v_mul_f32_e32 v49, v53, v47
	global_store_dword v[42:43], v47, off offset:256
	global_store_dword v[42:43], v49, off offset:512
	v_cvt_pk_bf16_f32 v42, v46, s0
	global_store_short v[44:45], v42, off offset:896
	v_cvt_pk_bf16_f32 v42, v48, s0
	global_store_short v[44:45], v42, off offset:1024
	v_lshlrev_b64 v[42:43], 9, v[40:41]
	s_waitcnt lgkmcnt(0)
	v_cvt_pk_bf16_f32 v44, v109, s0
	v_lshl_add_u64 v[42:43], v[12:13], 0, v[42:43]
	global_store_short v[42:43], v44, off
	s_and_saveexec_b64 s[4:5], s[8:9]
	s_cbranch_execz .LBB0_1060
	v_mov_b32_e32 v42, s14
	v_mov_b32_e32 v43, s15
	v_pk_add_f32 v[42:43], s[2:3], v[42:43]
	v_lshl_add_u64 v[40:41], v[40:41], 4, v[14:15]
	v_add_f32_e32 v42, v42, v43
	global_store_dword v[40:41], v42, off
	s_branch .LBB0_1060
